# GEMM loops: loop-invariant LDS fragment base addresses computed once per tile in the preamble instead of at the head of every K-tile section
# speedup vs baseline: 1.0040x; 1.0007x over previous
; DEV int tidx() { int t = threadIdx.x; asm volatile("" : "+v"(t)); return t; }
; #define G_LOAD(RA, RB, KT) { _Pragma("unroll") for (int i = 0; i < 4; i++) { \
;       RA[i] = *(const u32x4*)(Ap + (size_t)(i * 32) * lda + (KT) * 64); RB[i] = *(const u32x4*)(Bp + (size_t)(i * 32) * ldb + (KT) * 64); } }
; template <class Epi>
; DEV void gemm_tile(const bf16_t* __restrict__ A, int lda, const bf16_t* __restrict__ Bt, int ldb, int K, int m0, int n0,
;                    Epi& epi, char* smem) {
;     ...
;   const int tid = tidx(), lane = tid & 63, w = tid >> 6, wm = w >> 1, wn = w & 1;
;   const int l15 = lane & 15, quad = lane >> 4;
;   f32x4 acc[4][4];
; #pragma unroll
;   for (int i = 0; i < 4; i++)
; #pragma unroll
;     for (int j = 0; j < 4; j++) acc[i][j] = (f32x4){0.f, 0.f, 0.f, 0.f};
;   u32x4 ra0[4], rb0[4], ra1[4], rb1[4];
;   const int nk = K >> 6;
;   const int lrow = tid >> 3, lcc = tid & 7;
;   const bf16_t* Ap = A + (size_t)(m0 + lrow) * lda + lcc * 8;
;   const bf16_t* Bp = Bt + (size_t)(n0 + lrow) * ldb + lcc * 8;
;     ...
;   G_LOAD(ra0, rb0, 0);
;   G_LOAD(ra1, rb1, 1);
.LBB0_179:
	s_ashr_i32 s13, s1, 6
	s_and_b32 s2, s1, 7
	s_and_b32 s3, s13, -8
	s_or_b32 s2, s3, s2
	s_lshr_b32 s3, s1, 31
	s_add_i32 s3, s2, s3
	s_ashr_i32 s12, s3, 1
	s_lshl_b32 s3, s12, 3
	s_bfe_u32 s14, s1, 0x30006
	s_or_b32 s3, s3, s14
	s_cmpk_gt_i32 s3, 0x7f
	s_cbranch_scc1 .LBB0_178
	v_mov_b32_e32 v145, v195
	s_lshr_b32 s14, s1, 6
	s_lshl_b32 s2, s2, 3
	s_lshl_b32 s18, s12, 4
	s_lshl_b32 s3, s3, 7
	s_and_b32 s15, s0, 7
	v_ashrrev_i32_e32 v66, 3, v145
	s_and_b32 s14, s14, 7
	s_sub_i32 s2, s2, s18
	s_movk_i32 s20, 0x880
	s_bfe_u32 s19, s1, 0x30003
	v_add_u32_e32 v0, s3, v66
	v_mov_b64_e32 v[2:3], s[10:11]
	s_lshl_b32 s16, s15, 3
	s_lshl_b32 s17, s14, 7
	s_or_b32 s2, s2, s19
	v_mad_i64_i32 v[2:3], s[14:15], v0, s20, v[2:3]
	v_lshlrev_b32_e32 v0, 4, v145
	s_lshl_b32 s2, s2, 7
	v_and_b32_e32 v0, 0x70, v0
	v_lshl_add_u64 v[6:7], v[2:3], 0, v[0:1]
	v_add_u32_e32 v4, s2, v66
	v_mov_b64_e32 v[2:3], s[8:9]
	v_mad_i64_i32 v[2:3], s[14:15], v4, s20, v[2:3]
	s_mov_b32 s14, 0x11000
	s_waitcnt vmcnt(21)
	v_add_co_u32_e32 v22, vcc, s14, v6
	v_lshl_add_u64 v[14:15], v[2:3], 0, v[0:1]
	s_nop 0
	v_addc_co_u32_e32 v23, vcc, 0, v7, vcc
	s_waitcnt vmcnt(20)
	v_add_co_u32_e32 v30, vcc, s14, v14
	s_mov_b32 s14, 0x22000
	s_nop 0
	v_addc_co_u32_e32 v31, vcc, 0, v15, vcc
	s_waitcnt vmcnt(19)
	v_add_co_u32_e32 v38, vcc, s14, v6
	s_lshl_b32 s13, s13, 3
	s_nop 0
	v_addc_co_u32_e32 v39, vcc, 0, v7, vcc
	s_waitcnt vmcnt(18)
	v_add_co_u32_e32 v46, vcc, s14, v14
	s_mov_b32 s14, 0x33000
	s_nop 0
	v_addc_co_u32_e32 v47, vcc, 0, v15, vcc
	s_waitcnt vmcnt(17)
	v_add_co_u32_e32 v54, vcc, s14, v6
	s_and_b32 s13, s13, 0x1ffffc0
	s_nop 0
	v_addc_co_u32_e32 v55, vcc, 0, v7, vcc
	s_waitcnt vmcnt(16)
	v_add_co_u32_e32 v62, vcc, s14, v14
	s_or_b32 s13, s13, s16
	s_nop 0
	v_addc_co_u32_e32 v63, vcc, 0, v15, vcc
	global_load_dwordx4 v[2:5], v[6:7], off
	s_nop 0
	global_load_dwordx4 v[10:13], v[14:15], off
	s_nop 0
	global_load_dwordx4 v[18:21], v[22:23], off
	s_nop 0
	global_load_dwordx4 v[26:29], v[30:31], off
	s_nop 0
	global_load_dwordx4 v[34:37], v[38:39], off
	s_nop 0
	global_load_dwordx4 v[42:45], v[46:47], off
	s_nop 0
	global_load_dwordx4 v[50:53], v[54:55], off
	s_nop 0
	global_load_dwordx4 v[58:61], v[62:63], off
	s_nop 0
	global_load_dwordx4 v[6:9], v[6:7], off offset:128
	s_nop 0
	global_load_dwordx4 v[14:17], v[14:15], off offset:128
	s_nop 0
	global_load_dwordx4 v[22:25], v[22:23], off offset:128
	s_nop 0
	global_load_dwordx4 v[30:33], v[30:31], off offset:128
	s_nop 0
	global_load_dwordx4 v[38:41], v[38:39], off offset:128
	s_nop 0
	global_load_dwordx4 v[46:49], v[46:47], off offset:128
	s_nop 0
	global_load_dwordx4 v[54:57], v[54:55], off offset:128
	s_nop 0
	global_load_dwordx4 v[62:65], v[62:63], off offset:128
	s_or_b32 s13, s13, s19
	v_mad_u64_u32 v[134:135], s[14:15], v66, s36, v[0:1]
	s_sub_i32 s13, s13, s18
	v_ashrrev_i32_e32 v67, 1, v145
	s_lshl_b32 s14, s13, 7
	s_lshl_b32 s12, s12, 10
	v_and_b32_e32 v146, 0xffffffc0, v67
	v_ashrrev_i32_e32 v67, 31, v66
	s_ashr_i32 s15, s14, 31
	s_or_b32 s12, s17, s12
	s_movk_i32 s19, 0x880
	v_lshl_add_u64 v[68:69], v[66:67], 0, s[14:15]
	v_mov_b64_e32 v[70:71], s[28:29]
	v_add_u32_e32 v66, s12, v66
	v_and_b32_e32 v0, 7, v145
	v_mad_u64_u32 v[136:137], s[14:15], v68, s19, v[70:71]
	v_mad_i64_i32 v[138:139], s[12:13], v66, s19, v[70:71]
	v_mov_b32_e32 v118, 0
	v_and_b32_e32 v144, 64, v145
	v_lshlrev_b32_e32 v0, 4, v0
	v_mad_i32_i24 v137, v69, s19, v137
	s_mov_b32 s12, -2
	v_mov_b32_e32 v119, v118
	v_mov_b32_e32 v120, v118
	v_mov_b32_e32 v121, v118
	v_mov_b32_e32 v126, v118
	v_mov_b32_e32 v127, v118
	v_mov_b32_e32 v128, v118
	v_mov_b32_e32 v129, v118
	v_mov_b32_e32 v90, v118
	v_mov_b32_e32 v91, v118
	v_mov_b32_e32 v92, v118
	v_mov_b32_e32 v93, v118
	v_mov_b32_e32 v98, v118
	v_mov_b32_e32 v99, v118
	v_mov_b32_e32 v100, v118
	v_mov_b32_e32 v101, v118
	v_mov_b32_e32 v66, v118
	v_mov_b32_e32 v67, v118
	v_mov_b32_e32 v68, v118
	v_mov_b32_e32 v69, v118
	v_mov_b32_e32 v70, v118
	v_mov_b32_e32 v71, v118
	v_mov_b32_e32 v72, v118
	v_mov_b32_e32 v73, v118
	v_mov_b32_e32 v74, v118
	v_mov_b32_e32 v75, v118
	v_mov_b32_e32 v76, v118
	v_mov_b32_e32 v77, v118
	v_mov_b32_e32 v82, v118
	v_mov_b32_e32 v83, v118
	v_mov_b32_e32 v84, v118
	v_mov_b32_e32 v85, v118
	v_mov_b32_e32 v78, v118
	v_mov_b32_e32 v79, v118
	v_mov_b32_e32 v80, v118
	v_mov_b32_e32 v81, v118
	v_mov_b32_e32 v86, v118
	v_mov_b32_e32 v87, v118
	v_mov_b32_e32 v88, v118
	v_mov_b32_e32 v89, v118
	v_mov_b32_e32 v94, v118
	v_mov_b32_e32 v95, v118
	v_mov_b32_e32 v96, v118
	v_mov_b32_e32 v97, v118
	v_mov_b32_e32 v102, v118
	v_mov_b32_e32 v103, v118
	v_mov_b32_e32 v104, v118
	v_mov_b32_e32 v105, v118
	v_mov_b32_e32 v110, v118
	v_mov_b32_e32 v111, v118
	v_mov_b32_e32 v112, v118
	v_mov_b32_e32 v113, v118
	v_mov_b32_e32 v114, v118
	v_mov_b32_e32 v115, v118
	v_mov_b32_e32 v116, v118
	v_mov_b32_e32 v117, v118
	v_mov_b32_e32 v122, v118
	v_mov_b32_e32 v123, v118
	v_mov_b32_e32 v124, v118
	v_mov_b32_e32 v125, v118
	v_mov_b32_e32 v106, v118
	v_mov_b32_e32 v107, v118
	v_mov_b32_e32 v108, v118
	v_mov_b32_e32 v109, v118
	v_mov_b32_e32 v130, v195
	v_and_b32_e32 v135, 15, v130
	v_or_b32_e32 v131, v135, v144
	v_and_b32_e32 v148, 48, v130
	v_mul_u32_u24_e32 v130, 0x50, v131
	v_lshl_add_u32 v147, v130, 1, v148
	v_or_b32_e32 v135, v135, v146
	v_mad_u32_u24 v238, v135, s36, v148
	s_branch .LBB0_182
; DEV f32x4 mfma16(bf16x8 a, bf16x8 b, f32x4 c) { return __builtin_amdgcn_mfma_f32_16x16x32_bf16(a, b, c, 0, 0, 0); }
; #define G_LOAD(RA, RB, KT) { _Pragma("unroll") for (int i = 0; i < 4; i++) { \
;       RA[i] = *(const u32x4*)(Ap + (size_t)(i * 32) * lda + (KT) * 64); RB[i] = *(const u32x4*)(Bp + (size_t)(i * 32) * ldb + (KT) * 64); } }
; template <int TI, int TJ, int KS>
; DEV void mfma_lds(const bf16_t* Arows, int lda, const bf16_t* Brows, int ldb, int i0, int j0, f32x4 (&acc)[TI][TJ]) {
;     ...
;   for (int ks = 0; ks < KS; ks++) {
;     bf16x8 af[TI], bfr[TJ];
; #pragma unroll
;     for (int i = 0; i < TI; i++) af[i] = *(const bf16x8*)(Arows + (i0 + i * 16 + l15) * lda + ks * 32 + quad * 8);
; #pragma unroll
;     for (int j = 0; j < TJ; j++) bfr[j] = *(const bf16x8*)(Brows + (j0 + j * 16 + l15) * ldb + ks * 32 + quad * 8);
; #pragma unroll
;     for (int i = 0; i < TI; i++)
; #pragma unroll
;       for (int j = 0; j < TJ; j++) acc[i][j] = mfma16(af[i], bfr[j], acc[i][j]);
; template <class Epi>
; DEV void gemm_tile(const bf16_t* __restrict__ A, int lda, const bf16_t* __restrict__ Bt, int ldb, int K, int m0, int n0,
;                    Epi& epi, char* smem) {
;     ...
;     if (kt + 3 < nk) G_LOAD(ra1, rb1, kt + 3);
;     mfma_lds<4, 4, 2>(Bs, GLD, As, GLD, wn * 64, wm * 64, acc);
.LBB0_181:
	v_lshl_add_u64 v[136:137], v[136:137], 0, s[34:35]
	v_lshl_add_u64 v[138:139], v[138:139], 0, s[34:35]
	s_andn2_b64 vcc, exec, s[14:15]
	ds_read_b128 v[148:151], v147 offset:20480
	ds_read_b128 v[164:167], v238
	ds_read_b128 v[168:171], v238 offset:2560
	ds_read_b128 v[172:175], v238 offset:5120
	ds_read_b128 v[176:179], v238 offset:7680
	ds_read_b128 v[152:155], v147 offset:23040
	ds_read_b128 v[156:159], v147 offset:25600
	ds_read_b128 v[160:163], v147 offset:28160
	ds_read_b128 v[180:183], v238 offset:64
	ds_read_b128 v[184:187], v238 offset:2624
	s_waitcnt lgkmcnt(8)
	v_mfma_f32_16x16x32_bf16 v[106:109], v[148:151], v[164:167], v[106:109]
	s_waitcnt lgkmcnt(7)
	v_mfma_f32_16x16x32_bf16 v[122:125], v[148:151], v[168:171], v[122:125]
	s_waitcnt lgkmcnt(6)
	v_mfma_f32_16x16x32_bf16 v[114:117], v[148:151], v[172:175], v[114:117]
	s_waitcnt lgkmcnt(5)
	v_mfma_f32_16x16x32_bf16 v[110:113], v[148:151], v[176:179], v[110:113]
	ds_read_b128 v[148:151], v147 offset:20544
	s_waitcnt lgkmcnt(5)
	v_mfma_f32_16x16x32_bf16 v[102:105], v[152:155], v[164:167], v[102:105]
	v_mfma_f32_16x16x32_bf16 v[94:97], v[152:155], v[168:171], v[94:97]
	v_mfma_f32_16x16x32_bf16 v[86:89], v[152:155], v[172:175], v[86:89]
	v_mfma_f32_16x16x32_bf16 v[78:81], v[152:155], v[176:179], v[78:81]
	ds_read_b128 v[152:155], v147 offset:23104
	s_waitcnt lgkmcnt(5)
	v_mfma_f32_16x16x32_bf16 v[82:85], v[156:159], v[164:167], v[82:85]
	v_mfma_f32_16x16x32_bf16 v[74:77], v[156:159], v[168:171], v[74:77]
	v_mfma_f32_16x16x32_bf16 v[70:73], v[156:159], v[172:175], v[70:73]
	v_mfma_f32_16x16x32_bf16 v[66:69], v[156:159], v[176:179], v[66:69]
	ds_read_b128 v[156:159], v147 offset:25664
	s_waitcnt lgkmcnt(5)
	v_mfma_f32_16x16x32_bf16 v[126:129], v[160:163], v[172:175], v[126:129]
	v_mfma_f32_16x16x32_bf16 v[118:121], v[160:163], v[176:179], v[118:121]
	ds_read_b128 v[172:175], v238 offset:5184
	ds_read_b128 v[176:179], v238 offset:7744
	v_mfma_f32_16x16x32_bf16 v[98:101], v[160:163], v[164:167], v[98:101]
	v_mfma_f32_16x16x32_bf16 v[90:93], v[160:163], v[168:171], v[90:93]
	ds_read_b128 v[160:163], v147 offset:28224
	s_waitcnt lgkmcnt(5)
	v_mfma_f32_16x16x32_bf16 v[106:109], v[148:151], v[180:183], v[106:109]
	s_waitcnt lgkmcnt(4)
	v_mfma_f32_16x16x32_bf16 v[102:105], v[152:155], v[180:183], v[102:105]
	s_waitcnt lgkmcnt(3)
	v_mfma_f32_16x16x32_bf16 v[82:85], v[156:159], v[180:183], v[82:85]
	v_mfma_f32_16x16x32_bf16 v[122:125], v[148:151], v[184:187], v[122:125]
	v_mfma_f32_16x16x32_bf16 v[94:97], v[152:155], v[184:187], v[94:97]
	v_mfma_f32_16x16x32_bf16 v[74:77], v[156:159], v[184:187], v[74:77]
	s_waitcnt lgkmcnt(2)
	v_mfma_f32_16x16x32_bf16 v[114:117], v[148:151], v[172:175], v[114:117]
	v_mfma_f32_16x16x32_bf16 v[86:89], v[152:155], v[172:175], v[86:89]
	v_mfma_f32_16x16x32_bf16 v[70:73], v[156:159], v[172:175], v[70:73]
	s_waitcnt lgkmcnt(1)
	v_mfma_f32_16x16x32_bf16 v[110:113], v[148:151], v[176:179], v[110:113]
	v_mfma_f32_16x16x32_bf16 v[78:81], v[152:155], v[176:179], v[78:81]
	v_mfma_f32_16x16x32_bf16 v[66:69], v[156:159], v[176:179], v[66:69]
	s_waitcnt lgkmcnt(0)
	v_mfma_f32_16x16x32_bf16 v[98:101], v[160:163], v[180:183], v[98:101]
	v_mfma_f32_16x16x32_bf16 v[90:93], v[160:163], v[184:187], v[90:93]
	v_mfma_f32_16x16x32_bf16 v[126:129], v[160:163], v[172:175], v[126:129]
	v_mfma_f32_16x16x32_bf16 v[118:121], v[160:163], v[176:179], v[118:121]
	s_cbranch_vccz .LBB0_177

; DEV f32x4 mfma16(bf16x8 a, bf16x8 b, f32x4 c) { return __builtin_amdgcn_mfma_f32_16x16x32_bf16(a, b, c, 0, 0, 0); }
; #define G_LOAD(RA, RB, KT) { _Pragma("unroll") for (int i = 0; i < 4; i++) { \
;       RA[i] = *(const u32x4*)(Ap + (size_t)(i * 32) * lda + (KT) * 64); RB[i] = *(const u32x4*)(Bp + (size_t)(i * 32) * ldb + (KT) * 64); } }
; #define G_STORE(RA, RB) { _Pragma("unroll") for (int i = 0; i < 4; i++) { \
;       *(u32x4*)(As + (lrow + i * 32) * GLD + lcc * 8) = RA[i]; *(u32x4*)(Bs + (lrow + i * 32) * GLD + lcc * 8) = RB[i]; } }
; template <int TI, int TJ, int KS>
; DEV void mfma_lds(const bf16_t* Arows, int lda, const bf16_t* Brows, int ldb, int i0, int j0, f32x4 (&acc)[TI][TJ]) {
;     ...
;   for (int ks = 0; ks < KS; ks++) {
;     bf16x8 af[TI], bfr[TJ];
; #pragma unroll
;     for (int i = 0; i < TI; i++) af[i] = *(const bf16x8*)(Arows + (i0 + i * 16 + l15) * lda + ks * 32 + quad * 8);
; #pragma unroll
;     for (int j = 0; j < TJ; j++) bfr[j] = *(const bf16x8*)(Brows + (j0 + j * 16 + l15) * ldb + ks * 32 + quad * 8);
; #pragma unroll
;     for (int i = 0; i < TI; i++)
; #pragma unroll
;       for (int j = 0; j < TJ; j++) acc[i][j] = mfma16(af[i], bfr[j], acc[i][j]);
; template <class Epi>
; DEV void gemm_tile(const bf16_t* __restrict__ A, int lda, const bf16_t* __restrict__ Bt, int ldb, int K, int m0, int n0,
;                    Epi& epi, char* smem) {
;     ...
;     mfma_lds<4, 4, 2>(Bs, GLD, As, GLD, wn * 64, wm * 64, acc);
;     __syncthreads();
;     G_STORE(ra1, rb1);
;     __syncthreads();
;     if (kt + 3 < nk) G_LOAD(ra1, rb1, kt + 3);
.LBB0_184:
	s_cmp_gt_u32 s12, 12
	ds_read_b128 v[148:151], v147 offset:20480
	ds_read_b128 v[164:167], v238
	ds_read_b128 v[168:171], v238 offset:2560
	ds_read_b128 v[172:175], v238 offset:5120
	ds_read_b128 v[176:179], v238 offset:7680
	ds_read_b128 v[152:155], v147 offset:23040
	ds_read_b128 v[156:159], v147 offset:25600
	ds_read_b128 v[160:163], v147 offset:28160
	ds_read_b128 v[180:183], v238 offset:64
	ds_read_b128 v[184:187], v238 offset:2624
	s_waitcnt lgkmcnt(8)
	v_mfma_f32_16x16x32_bf16 v[106:109], v[148:151], v[164:167], v[106:109]
	s_waitcnt lgkmcnt(7)
	v_mfma_f32_16x16x32_bf16 v[122:125], v[148:151], v[168:171], v[122:125]
	s_waitcnt lgkmcnt(6)
	v_mfma_f32_16x16x32_bf16 v[114:117], v[148:151], v[172:175], v[114:117]
	s_waitcnt lgkmcnt(5)
	v_mfma_f32_16x16x32_bf16 v[110:113], v[148:151], v[176:179], v[110:113]
	ds_read_b128 v[148:151], v147 offset:20544
	s_waitcnt lgkmcnt(5)
	v_mfma_f32_16x16x32_bf16 v[102:105], v[152:155], v[164:167], v[102:105]
	v_mfma_f32_16x16x32_bf16 v[94:97], v[152:155], v[168:171], v[94:97]
	v_mfma_f32_16x16x32_bf16 v[86:89], v[152:155], v[172:175], v[86:89]
	v_mfma_f32_16x16x32_bf16 v[78:81], v[152:155], v[176:179], v[78:81]
	ds_read_b128 v[152:155], v147 offset:23104
	s_waitcnt lgkmcnt(5)
	v_mfma_f32_16x16x32_bf16 v[82:85], v[156:159], v[164:167], v[82:85]
	v_mfma_f32_16x16x32_bf16 v[74:77], v[156:159], v[168:171], v[74:77]
	v_mfma_f32_16x16x32_bf16 v[70:73], v[156:159], v[172:175], v[70:73]
	v_mfma_f32_16x16x32_bf16 v[66:69], v[156:159], v[176:179], v[66:69]
	ds_read_b128 v[156:159], v147 offset:25664
	s_waitcnt lgkmcnt(5)
	v_mfma_f32_16x16x32_bf16 v[126:129], v[160:163], v[172:175], v[126:129]
	v_mfma_f32_16x16x32_bf16 v[118:121], v[160:163], v[176:179], v[118:121]
	ds_read_b128 v[172:175], v238 offset:5184
	ds_read_b128 v[176:179], v238 offset:7744
	v_mfma_f32_16x16x32_bf16 v[98:101], v[160:163], v[164:167], v[98:101]
	v_mfma_f32_16x16x32_bf16 v[90:93], v[160:163], v[168:171], v[90:93]
	ds_read_b128 v[160:163], v147 offset:28224
	s_waitcnt lgkmcnt(5)
	v_mfma_f32_16x16x32_bf16 v[106:109], v[148:151], v[180:183], v[106:109]
	s_waitcnt lgkmcnt(4)
	v_mfma_f32_16x16x32_bf16 v[102:105], v[152:155], v[180:183], v[102:105]
	s_waitcnt lgkmcnt(3)
	v_mfma_f32_16x16x32_bf16 v[82:85], v[156:159], v[180:183], v[82:85]
	v_mfma_f32_16x16x32_bf16 v[122:125], v[148:151], v[184:187], v[122:125]
	v_mfma_f32_16x16x32_bf16 v[94:97], v[152:155], v[184:187], v[94:97]
	v_mfma_f32_16x16x32_bf16 v[74:77], v[156:159], v[184:187], v[74:77]
	s_waitcnt lgkmcnt(2)
	v_mfma_f32_16x16x32_bf16 v[114:117], v[148:151], v[172:175], v[114:117]
	v_mfma_f32_16x16x32_bf16 v[86:89], v[152:155], v[172:175], v[86:89]
	v_mfma_f32_16x16x32_bf16 v[70:73], v[156:159], v[172:175], v[70:73]
	s_waitcnt lgkmcnt(1)
	v_mfma_f32_16x16x32_bf16 v[110:113], v[148:151], v[176:179], v[110:113]
	v_mfma_f32_16x16x32_bf16 v[78:81], v[152:155], v[176:179], v[78:81]
	v_mfma_f32_16x16x32_bf16 v[66:69], v[156:159], v[176:179], v[66:69]
	s_waitcnt lgkmcnt(0)
	v_mfma_f32_16x16x32_bf16 v[98:101], v[160:163], v[180:183], v[98:101]
	s_barrier
	v_mfma_f32_16x16x32_bf16 v[90:93], v[160:163], v[184:187], v[90:93]
	s_waitcnt vmcnt(8)
	ds_write_b128 v134, v[6:9]
	ds_write_b128 v134, v[14:17] offset:20480
	ds_write_b128 v134, v[22:25] offset:5120
	ds_write_b128 v134, v[30:33] offset:25600
	ds_write_b128 v134, v[38:41] offset:10240
	ds_write_b128 v134, v[46:49] offset:30720
	ds_write_b128 v134, v[54:57] offset:15360
	ds_write_b128 v134, v[62:65] offset:35840
	v_mfma_f32_16x16x32_bf16 v[126:129], v[160:163], v[172:175], v[126:129]
	s_waitcnt lgkmcnt(0)
	s_barrier
	v_mfma_f32_16x16x32_bf16 v[118:121], v[160:163], v[176:179], v[118:121]
	s_cbranch_scc1 .LBB0_181
	v_add_co_u32_e32 v6, vcc, 0x4200000, v142
	s_nop 1
	v_addc_co_u32_e32 v7, vcc, 0, v143, vcc
	v_add_co_u32_e32 v14, vcc, 0xba00000, v140
	global_load_dwordx4 v[6:9], v[6:7], off offset:384
	s_nop 0
	v_addc_co_u32_e32 v15, vcc, 0, v141, vcc
	v_add_co_u32_e32 v22, vcc, 0x4211000, v142
	global_load_dwordx4 v[14:17], v[14:15], off offset:384
	s_nop 0
	v_addc_co_u32_e32 v23, vcc, 0, v143, vcc
	v_add_co_u32_e32 v30, vcc, 0xba11000, v140
	global_load_dwordx4 v[22:25], v[22:23], off offset:384
	s_nop 0
	v_addc_co_u32_e32 v31, vcc, 0, v141, vcc
	v_add_co_u32_e32 v38, vcc, 0x4222000, v142
	global_load_dwordx4 v[30:33], v[30:31], off offset:384
	s_nop 0
	v_addc_co_u32_e32 v39, vcc, 0, v143, vcc
	v_add_co_u32_e32 v46, vcc, 0xba22000, v140
	global_load_dwordx4 v[38:41], v[38:39], off offset:384
	s_nop 0
	v_addc_co_u32_e32 v47, vcc, 0, v141, vcc
	v_add_co_u32_e32 v54, vcc, 0x4233000, v142
	global_load_dwordx4 v[46:49], v[46:47], off offset:384
	s_nop 0
	v_addc_co_u32_e32 v55, vcc, 0, v143, vcc
	v_add_co_u32_e32 v62, vcc, 0xba33000, v140
	global_load_dwordx4 v[54:57], v[54:55], off offset:384
	s_nop 0
	v_addc_co_u32_e32 v63, vcc, 0, v141, vcc
	global_load_dwordx4 v[62:65], v[62:63], off offset:384
	s_branch .LBB0_181

; DEV int tidx() { int t = threadIdx.x; asm volatile("" : "+v"(t)); return t; }
; #define G_LOAD(RA, RB, KT) { _Pragma("unroll") for (int i = 0; i < 4; i++) { \
;       RA[i] = *(const u32x4*)(Ap + (size_t)(i * 32) * lda + (KT) * 64); RB[i] = *(const u32x4*)(Bp + (size_t)(i * 32) * ldb + (KT) * 64); } }
; template <class Epi>
; DEV void gemm_tile(const bf16_t* __restrict__ A, int lda, const bf16_t* __restrict__ Bt, int ldb, int K, int m0, int n0,
;                    Epi& epi, char* smem) {
;     ...
;   const int tid = tidx(), lane = tid & 63, w = tid >> 6, wm = w >> 1, wn = w & 1;
;   const int l15 = lane & 15, quad = lane >> 4;
;   f32x4 acc[4][4];
; #pragma unroll
;   for (int i = 0; i < 4; i++)
; #pragma unroll
;     for (int j = 0; j < 4; j++) acc[i][j] = (f32x4){0.f, 0.f, 0.f, 0.f};
;   u32x4 ra0[4], rb0[4], ra1[4], rb1[4];
;   const int nk = K >> 6;
;   const int lrow = tid >> 3, lcc = tid & 7;
;   const bf16_t* Ap = A + (size_t)(m0 + lrow) * lda + lcc * 8;
;   const bf16_t* Bp = Bt + (size_t)(n0 + lrow) * ldb + lcc * 8;
;     ...
;   G_LOAD(ra0, rb0, 0);
;   G_LOAD(ra1, rb1, 1);
.LBB0_198:
	s_ashr_i32 s1, s12, 6
	s_and_b32 s0, s12, 7
	s_and_b32 s13, s1, 0x1ffffff8
	s_or_b32 s0, s13, s0
	s_lshl_b32 s0, s0, 3
	s_bfe_u32 s13, s12, 0x30006
	s_or_b32 s0, s0, s13
	s_cmpk_gt_i32 s0, 0x7f
	s_cbranch_scc1 .LBB0_197
	s_lshr_b32 s13, s12, 6
	v_mov_b32_e32 v141, v195
	s_bfe_u32 s16, s3, 0x30007
	s_and_b32 s20, s13, 7
	s_lshl_b32 s0, s0, 7
	s_lshl_b32 s13, s12, 4
	s_mul_i32 s18, s16, 0x44000
	v_ashrrev_i32_e32 v2, 3, v141
	s_and_b32 s16, s2, 7
	s_movk_i32 s21, 0x880
	s_and_b32 s13, s13, 0x380
	v_add_u32_e32 v0, s0, v2
	v_mov_b64_e32 v[4:5], s[14:15]
	s_lshl_b32 s19, s16, 3
	v_mad_i64_i32 v[4:5], s[16:17], v0, s21, v[4:5]
	v_lshlrev_b32_e32 v0, 4, v141
	v_add_u32_e32 v3, s13, v2
	v_mov_b64_e32 v[6:7], s[10:11]
	v_and_b32_e32 v0, 0x70, v0
	v_mad_i64_i32 v[6:7], s[16:17], v3, s21, v[6:7]
	v_lshl_add_u64 v[4:5], v[4:5], 0, v[0:1]
	s_mov_b32 s16, 0x11000
	v_add_co_u32_e32 v8, vcc, s16, v4
	v_lshl_add_u64 v[6:7], v[6:7], 0, v[0:1]
	s_nop 0
	v_addc_co_u32_e32 v9, vcc, 0, v5, vcc
	v_add_co_u32_e32 v10, vcc, s16, v6
	s_mov_b32 s16, 0x22000
	s_nop 0
	v_addc_co_u32_e32 v11, vcc, 0, v7, vcc
	v_add_co_u32_e32 v12, vcc, s16, v4
	v_ashrrev_i32_e32 v3, 1, v141
	s_nop 0
	v_addc_co_u32_e32 v13, vcc, 0, v5, vcc
	s_waitcnt vmcnt(22)
	v_add_co_u32_e32 v14, vcc, s16, v6
	s_mov_b32 s16, 0x33000
	s_nop 0
	v_addc_co_u32_e32 v15, vcc, 0, v7, vcc
	v_add_co_u32_e32 v16, vcc, s16, v4
	v_and_b32_e32 v142, 0xffffffc0, v3
	s_nop 0
	v_addc_co_u32_e32 v17, vcc, 0, v5, vcc
	v_add_co_u32_e32 v18, vcc, s16, v6
	v_mad_u64_u32 v[130:131], s[16:17], v2, s36, v[0:1]
	s_nop 0
	v_addc_co_u32_e32 v19, vcc, 0, v7, vcc
	global_load_dwordx4 v[42:45], v[4:5], off
	global_load_dwordx4 v[50:53], v[6:7], off
	global_load_dwordx4 v[58:61], v[8:9], off
	global_load_dwordx4 v[66:69], v[10:11], off
	global_load_dwordx4 v[78:81], v[12:13], off
	global_load_dwordx4 v[86:89], v[14:15], off
	global_load_dwordx4 v[94:97], v[16:17], off
	global_load_dwordx4 v[102:105], v[18:19], off
	global_load_dwordx4 v[46:49], v[4:5], off offset:128
	global_load_dwordx4 v[54:57], v[6:7], off offset:128
	global_load_dwordx4 v[62:65], v[8:9], off offset:128
	global_load_dwordx4 v[70:73], v[10:11], off offset:128
	global_load_dwordx4 v[82:85], v[12:13], off offset:128
	global_load_dwordx4 v[90:93], v[14:15], off offset:128
	global_load_dwordx4 v[98:101], v[16:17], off offset:128
	global_load_dwordx4 v[106:109], v[18:19], off offset:128
	s_add_u32 s16, s28, s18
	s_addc_u32 s17, s29, 0
	s_lshl_b32 s1, s1, 3
	s_and_b32 s1, s1, 0x1ffffc0
	v_mov_b64_e32 v[4:5], s[16:17]
	s_or_b32 s1, s1, s19
	v_mad_i64_i32 v[132:133], s[16:17], v2, s21, v[4:5]
	s_or_b32 s1, s1, s20
	s_lshl_b32 s16, s1, 7
	v_ashrrev_i32_e32 v3, 31, v2
	s_ashr_i32 s17, s16, 31
	v_lshl_add_u64 v[2:3], v[2:3], 0, s[16:17]
	v_mov_b64_e32 v[4:5], s[28:29]
	v_and_b32_e32 v0, 7, v141
	v_mad_u64_u32 v[134:135], s[16:17], v2, s21, v[4:5]
	v_mov_b32_e32 v2, 0
	v_and_b32_e32 v140, 64, v141
	v_lshlrev_b32_e32 v0, 4, v0
	v_mad_i32_i24 v135, v3, s21, v135
	s_movk_i32 s21, 0x2000
	s_mov_b32 s1, -2
	v_mov_b32_e32 v3, v2
	v_mov_b32_e32 v4, v2
	v_mov_b32_e32 v5, v2
	v_mov_b32_e32 v6, v2
	v_mov_b32_e32 v7, v2
	v_mov_b32_e32 v8, v2
	v_mov_b32_e32 v9, v2
	v_mov_b32_e32 v10, v2
	v_mov_b32_e32 v11, v2
	v_mov_b32_e32 v12, v2
	v_mov_b32_e32 v13, v2
	v_mov_b32_e32 v14, v2
	v_mov_b32_e32 v15, v2
	v_mov_b32_e32 v16, v2
	v_mov_b32_e32 v17, v2
	v_mov_b32_e32 v18, v2
	v_mov_b32_e32 v19, v2
	v_mov_b32_e32 v20, v2
	v_mov_b32_e32 v21, v2
	s_waitcnt vmcnt(37)
	v_mov_b32_e32 v22, v2
	v_mov_b32_e32 v23, v2
	v_mov_b32_e32 v24, v2
	v_mov_b32_e32 v25, v2
	v_mov_b32_e32 v26, v2
	v_mov_b32_e32 v27, v2
	v_mov_b32_e32 v28, v2
	v_mov_b32_e32 v29, v2
	s_waitcnt vmcnt(36)
	v_mov_b32_e32 v30, v2
	v_mov_b32_e32 v31, v2
	v_mov_b32_e32 v32, v2
	v_mov_b32_e32 v33, v2
	v_mov_b32_e32 v34, v2
	v_mov_b32_e32 v35, v2
	v_mov_b32_e32 v36, v2
	v_mov_b32_e32 v37, v2
	s_waitcnt vmcnt(35)
	v_mov_b32_e32 v38, v2
	v_mov_b32_e32 v39, v2
	v_mov_b32_e32 v40, v2
	v_mov_b32_e32 v41, v2
	v_mov_b32_e32 v74, v2
	v_mov_b32_e32 v75, v2
	v_mov_b32_e32 v76, v2
	v_mov_b32_e32 v77, v2
	v_mov_b32_e32 v110, v2
	v_mov_b32_e32 v111, v2
	v_mov_b32_e32 v112, v2
	v_mov_b32_e32 v113, v2
	v_mov_b32_e32 v114, v2
	v_mov_b32_e32 v115, v2
	v_mov_b32_e32 v116, v2
	v_mov_b32_e32 v117, v2
	v_mov_b32_e32 v118, v2
	v_mov_b32_e32 v119, v2
	v_mov_b32_e32 v120, v2
	v_mov_b32_e32 v121, v2
	v_mov_b32_e32 v122, v2
	v_mov_b32_e32 v123, v2
	v_mov_b32_e32 v124, v2
	v_mov_b32_e32 v125, v2
	v_mov_b32_e32 v126, v2
	v_mov_b32_e32 v127, v2
	v_mov_b32_e32 v128, v2
	v_mov_b32_e32 v129, v2
	v_mov_b32_e32 v131, v195
	v_and_b32_e32 v143, 15, v131
	v_or_b32_e32 v144, v143, v140
	v_and_b32_e32 v148, 48, v131
	v_mul_u32_u24_e32 v131, 0x50, v144
	v_lshl_add_u32 v131, v131, 1, v148
	v_or_b32_e32 v143, v143, v142
	v_mad_u32_u24 v238, v143, s36, v148
	s_branch .LBB0_201
; DEV f32x4 mfma16(bf16x8 a, bf16x8 b, f32x4 c) { return __builtin_amdgcn_mfma_f32_16x16x32_bf16(a, b, c, 0, 0, 0); }
; #define G_LOAD(RA, RB, KT) { _Pragma("unroll") for (int i = 0; i < 4; i++) { \
;       RA[i] = *(const u32x4*)(Ap + (size_t)(i * 32) * lda + (KT) * 64); RB[i] = *(const u32x4*)(Bp + (size_t)(i * 32) * ldb + (KT) * 64); } }
; template <int TI, int TJ, int KS>
; DEV void mfma_lds(const bf16_t* Arows, int lda, const bf16_t* Brows, int ldb, int i0, int j0, f32x4 (&acc)[TI][TJ]) {
;     ...
;   for (int ks = 0; ks < KS; ks++) {
;     bf16x8 af[TI], bfr[TJ];
; #pragma unroll
;     for (int i = 0; i < TI; i++) af[i] = *(const bf16x8*)(Arows + (i0 + i * 16 + l15) * lda + ks * 32 + quad * 8);
; #pragma unroll
;     for (int j = 0; j < TJ; j++) bfr[j] = *(const bf16x8*)(Brows + (j0 + j * 16 + l15) * ldb + ks * 32 + quad * 8);
; #pragma unroll
;     for (int i = 0; i < TI; i++)
; #pragma unroll
;       for (int j = 0; j < TJ; j++) acc[i][j] = mfma16(af[i], bfr[j], acc[i][j]);
; template <class Epi>
; DEV void gemm_tile(const bf16_t* __restrict__ A, int lda, const bf16_t* __restrict__ Bt, int ldb, int K, int m0, int n0,
;                    Epi& epi, char* smem) {
;     ...
;     if (kt + 3 < nk) G_LOAD(ra1, rb1, kt + 3);
;     mfma_lds<4, 4, 2>(Bs, GLD, As, GLD, wn * 64, wm * 64, acc);
.LBB0_200:
	v_lshl_add_u64 v[132:133], v[132:133], 0, s[34:35]
	v_lshl_add_u64 v[134:135], v[134:135], 0, s[34:35]
	s_and_b64 vcc, exec, s[16:17]
	ds_read_b128 v[144:147], v131 offset:20480
	ds_read_b128 v[160:163], v238
	ds_read_b128 v[164:167], v238 offset:2560
	ds_read_b128 v[168:171], v238 offset:5120
	ds_read_b128 v[172:175], v238 offset:7680
	ds_read_b128 v[148:151], v131 offset:23040
	ds_read_b128 v[152:155], v131 offset:25600
	ds_read_b128 v[156:159], v131 offset:28160
	ds_read_b128 v[176:179], v238 offset:64
	ds_read_b128 v[180:183], v238 offset:2624
	s_waitcnt lgkmcnt(8)
	v_mfma_f32_16x16x32_bf16 v[126:129], v[144:147], v[160:163], v[126:129]
	s_waitcnt lgkmcnt(7)
	v_mfma_f32_16x16x32_bf16 v[122:125], v[144:147], v[164:167], v[122:125]
	s_waitcnt lgkmcnt(6)
	v_mfma_f32_16x16x32_bf16 v[118:121], v[144:147], v[168:171], v[118:121]
	s_waitcnt lgkmcnt(5)
	v_mfma_f32_16x16x32_bf16 v[114:117], v[144:147], v[172:175], v[114:117]
	ds_read_b128 v[144:147], v131 offset:20544
	s_waitcnt lgkmcnt(5)
	v_mfma_f32_16x16x32_bf16 v[110:113], v[148:151], v[160:163], v[110:113]
	v_mfma_f32_16x16x32_bf16 v[74:77], v[148:151], v[164:167], v[74:77]
	v_mfma_f32_16x16x32_bf16 v[38:41], v[148:151], v[168:171], v[38:41]
	v_mfma_f32_16x16x32_bf16 v[34:37], v[148:151], v[172:175], v[34:37]
	ds_read_b128 v[148:151], v131 offset:23104
	s_waitcnt lgkmcnt(5)
	v_mfma_f32_16x16x32_bf16 v[30:33], v[152:155], v[160:163], v[30:33]
	v_mfma_f32_16x16x32_bf16 v[26:29], v[152:155], v[164:167], v[26:29]
	v_mfma_f32_16x16x32_bf16 v[22:25], v[152:155], v[168:171], v[22:25]
	v_mfma_f32_16x16x32_bf16 v[18:21], v[152:155], v[172:175], v[18:21]
	ds_read_b128 v[152:155], v131 offset:25664
	s_waitcnt lgkmcnt(5)
	v_mfma_f32_16x16x32_bf16 v[6:9], v[156:159], v[168:171], v[6:9]
	v_mfma_f32_16x16x32_bf16 v[2:5], v[156:159], v[172:175], v[2:5]
	ds_read_b128 v[168:171], v238 offset:5184
	ds_read_b128 v[172:175], v238 offset:7744
	v_mfma_f32_16x16x32_bf16 v[14:17], v[156:159], v[160:163], v[14:17]
	v_mfma_f32_16x16x32_bf16 v[10:13], v[156:159], v[164:167], v[10:13]
	ds_read_b128 v[156:159], v131 offset:28224
	s_waitcnt lgkmcnt(5)
	v_mfma_f32_16x16x32_bf16 v[126:129], v[144:147], v[176:179], v[126:129]
	s_waitcnt lgkmcnt(4)
	v_mfma_f32_16x16x32_bf16 v[110:113], v[148:151], v[176:179], v[110:113]
	s_waitcnt lgkmcnt(3)
	v_mfma_f32_16x16x32_bf16 v[30:33], v[152:155], v[176:179], v[30:33]
	v_mfma_f32_16x16x32_bf16 v[122:125], v[144:147], v[180:183], v[122:125]
	v_mfma_f32_16x16x32_bf16 v[74:77], v[148:151], v[180:183], v[74:77]
	v_mfma_f32_16x16x32_bf16 v[26:29], v[152:155], v[180:183], v[26:29]
	s_waitcnt lgkmcnt(2)
	v_mfma_f32_16x16x32_bf16 v[118:121], v[144:147], v[168:171], v[118:121]
	v_mfma_f32_16x16x32_bf16 v[38:41], v[148:151], v[168:171], v[38:41]
	v_mfma_f32_16x16x32_bf16 v[22:25], v[152:155], v[168:171], v[22:25]
	s_waitcnt lgkmcnt(1)
	v_mfma_f32_16x16x32_bf16 v[114:117], v[144:147], v[172:175], v[114:117]
	v_mfma_f32_16x16x32_bf16 v[34:37], v[148:151], v[172:175], v[34:37]
	v_mfma_f32_16x16x32_bf16 v[18:21], v[152:155], v[172:175], v[18:21]
	s_waitcnt lgkmcnt(0)
	v_mfma_f32_16x16x32_bf16 v[14:17], v[156:159], v[176:179], v[14:17]
	v_mfma_f32_16x16x32_bf16 v[10:13], v[156:159], v[180:183], v[10:13]
	v_mfma_f32_16x16x32_bf16 v[6:9], v[156:159], v[168:171], v[6:9]
	v_mfma_f32_16x16x32_bf16 v[2:5], v[156:159], v[172:175], v[2:5]
	s_cbranch_vccnz .LBB0_205

; DEV f32x4 mfma16(bf16x8 a, bf16x8 b, f32x4 c) { return __builtin_amdgcn_mfma_f32_16x16x32_bf16(a, b, c, 0, 0, 0); }
; #define G_LOAD(RA, RB, KT) { _Pragma("unroll") for (int i = 0; i < 4; i++) { \
;       RA[i] = *(const u32x4*)(Ap + (size_t)(i * 32) * lda + (KT) * 64); RB[i] = *(const u32x4*)(Bp + (size_t)(i * 32) * ldb + (KT) * 64); } }
; #define G_STORE(RA, RB) { _Pragma("unroll") for (int i = 0; i < 4; i++) { \
;       *(u32x4*)(As + (lrow + i * 32) * GLD + lcc * 8) = RA[i]; *(u32x4*)(Bs + (lrow + i * 32) * GLD + lcc * 8) = RB[i]; } }
; template <int TI, int TJ, int KS>
; DEV void mfma_lds(const bf16_t* Arows, int lda, const bf16_t* Brows, int ldb, int i0, int j0, f32x4 (&acc)[TI][TJ]) {
;     ...
;   for (int ks = 0; ks < KS; ks++) {
;     bf16x8 af[TI], bfr[TJ];
; #pragma unroll
;     for (int i = 0; i < TI; i++) af[i] = *(const bf16x8*)(Arows + (i0 + i * 16 + l15) * lda + ks * 32 + quad * 8);
; #pragma unroll
;     for (int j = 0; j < TJ; j++) bfr[j] = *(const bf16x8*)(Brows + (j0 + j * 16 + l15) * ldb + ks * 32 + quad * 8);
; #pragma unroll
;     for (int i = 0; i < TI; i++)
; #pragma unroll
;       for (int j = 0; j < TJ; j++) acc[i][j] = mfma16(af[i], bfr[j], acc[i][j]);
; template <class Epi>
; DEV void gemm_tile(const bf16_t* __restrict__ A, int lda, const bf16_t* __restrict__ Bt, int ldb, int K, int m0, int n0,
;                    Epi& epi, char* smem) {
;     ...
;     mfma_lds<4, 4, 2>(Bs, GLD, As, GLD, wn * 64, wm * 64, acc);
;     __syncthreads();
;     G_STORE(ra1, rb1);
;     __syncthreads();
;     if (kt + 3 < nk) G_LOAD(ra1, rb1, kt + 3);
.LBB0_203:
	s_cmp_gt_u32 s1, 12
	ds_read_b128 v[144:147], v131 offset:20480
	ds_read_b128 v[160:163], v238
	ds_read_b128 v[164:167], v238 offset:2560
	ds_read_b128 v[168:171], v238 offset:5120
	ds_read_b128 v[172:175], v238 offset:7680
	ds_read_b128 v[148:151], v131 offset:23040
	ds_read_b128 v[152:155], v131 offset:25600
	ds_read_b128 v[156:159], v131 offset:28160
	ds_read_b128 v[176:179], v238 offset:64
	ds_read_b128 v[180:183], v238 offset:2624
	s_waitcnt lgkmcnt(8)
	v_mfma_f32_16x16x32_bf16 v[126:129], v[144:147], v[160:163], v[126:129]
	s_waitcnt lgkmcnt(7)
	v_mfma_f32_16x16x32_bf16 v[122:125], v[144:147], v[164:167], v[122:125]
	s_waitcnt lgkmcnt(6)
	v_mfma_f32_16x16x32_bf16 v[118:121], v[144:147], v[168:171], v[118:121]
	s_waitcnt lgkmcnt(5)
	v_mfma_f32_16x16x32_bf16 v[114:117], v[144:147], v[172:175], v[114:117]
	ds_read_b128 v[144:147], v131 offset:20544
	s_waitcnt lgkmcnt(5)
	v_mfma_f32_16x16x32_bf16 v[110:113], v[148:151], v[160:163], v[110:113]
	v_mfma_f32_16x16x32_bf16 v[74:77], v[148:151], v[164:167], v[74:77]
	v_mfma_f32_16x16x32_bf16 v[38:41], v[148:151], v[168:171], v[38:41]
	v_mfma_f32_16x16x32_bf16 v[34:37], v[148:151], v[172:175], v[34:37]
	ds_read_b128 v[148:151], v131 offset:23104
	s_waitcnt lgkmcnt(5)
	v_mfma_f32_16x16x32_bf16 v[30:33], v[152:155], v[160:163], v[30:33]
	v_mfma_f32_16x16x32_bf16 v[26:29], v[152:155], v[164:167], v[26:29]
	v_mfma_f32_16x16x32_bf16 v[22:25], v[152:155], v[168:171], v[22:25]
	v_mfma_f32_16x16x32_bf16 v[18:21], v[152:155], v[172:175], v[18:21]
	ds_read_b128 v[152:155], v131 offset:25664
	s_waitcnt lgkmcnt(5)
	v_mfma_f32_16x16x32_bf16 v[6:9], v[156:159], v[168:171], v[6:9]
	v_mfma_f32_16x16x32_bf16 v[2:5], v[156:159], v[172:175], v[2:5]
	ds_read_b128 v[168:171], v238 offset:5184
	ds_read_b128 v[172:175], v238 offset:7744
	v_mfma_f32_16x16x32_bf16 v[14:17], v[156:159], v[160:163], v[14:17]
	v_mfma_f32_16x16x32_bf16 v[10:13], v[156:159], v[164:167], v[10:13]
	ds_read_b128 v[156:159], v131 offset:28224
	s_waitcnt lgkmcnt(5)
	v_mfma_f32_16x16x32_bf16 v[126:129], v[144:147], v[176:179], v[126:129]
	s_waitcnt lgkmcnt(4)
	v_mfma_f32_16x16x32_bf16 v[110:113], v[148:151], v[176:179], v[110:113]
	s_waitcnt lgkmcnt(3)
	v_mfma_f32_16x16x32_bf16 v[30:33], v[152:155], v[176:179], v[30:33]
	v_mfma_f32_16x16x32_bf16 v[122:125], v[144:147], v[180:183], v[122:125]
	v_mfma_f32_16x16x32_bf16 v[74:77], v[148:151], v[180:183], v[74:77]
	v_mfma_f32_16x16x32_bf16 v[26:29], v[152:155], v[180:183], v[26:29]
	s_waitcnt lgkmcnt(2)
	v_mfma_f32_16x16x32_bf16 v[118:121], v[144:147], v[168:171], v[118:121]
	v_mfma_f32_16x16x32_bf16 v[38:41], v[148:151], v[168:171], v[38:41]
	v_mfma_f32_16x16x32_bf16 v[22:25], v[152:155], v[168:171], v[22:25]
	s_waitcnt lgkmcnt(1)
	v_mfma_f32_16x16x32_bf16 v[114:117], v[144:147], v[172:175], v[114:117]
	v_mfma_f32_16x16x32_bf16 v[34:37], v[148:151], v[172:175], v[34:37]
	v_mfma_f32_16x16x32_bf16 v[18:21], v[152:155], v[172:175], v[18:21]
	s_waitcnt lgkmcnt(0)
	v_mfma_f32_16x16x32_bf16 v[14:17], v[156:159], v[176:179], v[14:17]
	s_barrier
	v_mfma_f32_16x16x32_bf16 v[10:13], v[156:159], v[180:183], v[10:13]
	s_waitcnt vmcnt(8)
	ds_write_b128 v130, v[46:49]
	ds_write_b128 v130, v[54:57] offset:20480
	ds_write_b128 v130, v[62:65] offset:5120
	ds_write_b128 v130, v[70:73] offset:25600
	ds_write_b128 v130, v[82:85] offset:10240
	ds_write_b128 v130, v[90:93] offset:30720
	ds_write_b128 v130, v[98:101] offset:15360
	ds_write_b128 v130, v[106:109] offset:35840
	v_mfma_f32_16x16x32_bf16 v[6:9], v[156:159], v[168:171], v[6:9]
	s_waitcnt lgkmcnt(0)
	s_barrier
	v_mfma_f32_16x16x32_bf16 v[2:5], v[156:159], v[172:175], v[2:5]
	s_cbranch_scc1 .LBB0_200
	v_add_co_u32_e32 v46, vcc, 0x4200000, v138
	s_nop 1
	v_addc_co_u32_e32 v47, vcc, 0, v139, vcc
	v_add_co_u32_e32 v54, vcc, 0xb3a0000, v136
	global_load_dwordx4 v[46:49], v[46:47], off offset:384
	s_nop 0
	v_addc_co_u32_e32 v55, vcc, 0, v137, vcc
	v_add_co_u32_e32 v62, vcc, 0x4211000, v138
	global_load_dwordx4 v[54:57], v[54:55], off offset:384
	s_nop 0
	v_addc_co_u32_e32 v63, vcc, 0, v139, vcc
	v_add_co_u32_e32 v70, vcc, 0xb3b1000, v136
	global_load_dwordx4 v[62:65], v[62:63], off offset:384
	s_nop 0
	v_addc_co_u32_e32 v71, vcc, 0, v137, vcc
	v_add_co_u32_e32 v82, vcc, 0x4222000, v138
	global_load_dwordx4 v[70:73], v[70:71], off offset:384
	s_nop 0
	v_addc_co_u32_e32 v83, vcc, 0, v139, vcc
	v_add_co_u32_e32 v90, vcc, 0xb3c2000, v136
	global_load_dwordx4 v[82:85], v[82:83], off offset:384
	s_nop 0
	v_addc_co_u32_e32 v91, vcc, 0, v137, vcc
	v_add_co_u32_e32 v98, vcc, 0x4233000, v138
	global_load_dwordx4 v[90:93], v[90:91], off offset:384
	s_nop 0
	v_addc_co_u32_e32 v99, vcc, 0, v139, vcc
	v_add_co_u32_e32 v106, vcc, 0xb3d3000, v136
	global_load_dwordx4 v[98:101], v[98:99], off offset:384
	s_nop 0
	v_addc_co_u32_e32 v107, vcc, 0, v137, vcc
	global_load_dwordx4 v[106:109], v[106:107], off offset:384
	s_branch .LBB0_200

; DEV int tidx() { int t = threadIdx.x; asm volatile("" : "+v"(t)); return t; }
; #define G_LOAD(RA, RB, KT) { _Pragma("unroll") for (int i = 0; i < 4; i++) { \
;       RA[i] = *(const u32x4*)(Ap + (size_t)(i * 32) * lda + (KT) * 64); RB[i] = *(const u32x4*)(Bp + (size_t)(i * 32) * ldb + (KT) * 64); } }
; template <class Epi>
; DEV void gemm_tile(const bf16_t* __restrict__ A, int lda, const bf16_t* __restrict__ Bt, int ldb, int K, int m0, int n0,
;                    Epi& epi, char* smem) {
;     ...
;   const int tid = tidx(), lane = tid & 63, w = tid >> 6, wm = w >> 1, wn = w & 1;
;   const int l15 = lane & 15, quad = lane >> 4;
;   f32x4 acc[4][4];
; #pragma unroll
;   for (int i = 0; i < 4; i++)
; #pragma unroll
;     for (int j = 0; j < 4; j++) acc[i][j] = (f32x4){0.f, 0.f, 0.f, 0.f};
;   u32x4 ra0[4], rb0[4], ra1[4], rb1[4];
;   const int nk = K >> 6;
;   const int lrow = tid >> 3, lcc = tid & 7;
;   const bf16_t* Ap = A + (size_t)(m0 + lrow) * lda + lcc * 8;
;   const bf16_t* Bp = Bt + (size_t)(n0 + lrow) * ldb + lcc * 8;
;     ...
;   G_LOAD(ra0, rb0, 0);
;   G_LOAD(ra1, rb1, 1);
; DEV void phase_gemm_hgin(const Params& p, char* smem) {
;     ...
;   const int items = (MT / 128) * 40;
;   for (int item = blockIdx.x; item < items; item += gridDim.x) {
;     int mt = item / 40, nt = item - mt * 40;
;     gemm_tile(WSP(bf16_t, OFF_H), LDH, WSP(bf16_t, S_WHGIN), LDH, 1024, mt * 128, nt * 128, epi, smem);
.LBB0_323:
	s_mul_hi_i32 s0, s21, 0x66666667
	s_lshr_b32 s1, s0, 31
	s_ashr_i32 s0, s0, 4
	s_add_i32 s1, s0, s1
	s_mul_i32 s0, s1, 0xffffffd8
	s_add_i32 s0, s0, s21
	v_mov_b32_e32 v140, v195
	s_lshl_b32 s12, s1, 7
	s_lshl_b32 s13, s0, 7
	v_mov_b64_e32 v[2:3], s[28:29]
	v_ashrrev_i32_e32 v18, 3, v140
	v_add_u32_e32 v19, s12, v18
	s_movk_i32 s10, 0x880
	v_lshlrev_b32_e32 v0, 4, v140
	v_add_u32_e32 v6, s13, v18
	v_mov_b64_e32 v[4:5], s[18:19]
	v_mad_i64_i32 v[2:3], s[6:7], v19, s10, v[2:3]
	v_and_b32_e32 v0, 0x70, v0
	v_mad_i64_i32 v[4:5], s[6:7], v6, s10, v[4:5]
	v_lshl_add_u64 v[2:3], v[2:3], 0, v[0:1]
	s_mov_b32 s6, 0x11000
	v_add_co_u32_e32 v6, vcc, s6, v2
	v_lshl_add_u64 v[4:5], v[4:5], 0, v[0:1]
	s_nop 0
	v_addc_co_u32_e32 v7, vcc, 0, v3, vcc
	v_add_co_u32_e32 v8, vcc, s6, v4
	s_mov_b32 s6, 0x22000
	s_nop 0
	v_addc_co_u32_e32 v9, vcc, 0, v5, vcc
	v_add_co_u32_e32 v10, vcc, s6, v2
	s_mulk_i32 s1, 0x1400
	s_nop 0
	v_addc_co_u32_e32 v11, vcc, 0, v3, vcc
	v_add_co_u32_e32 v12, vcc, s6, v4
	s_mov_b32 s6, 0x33000
	s_nop 0
	v_addc_co_u32_e32 v13, vcc, 0, v5, vcc
	s_waitcnt vmcnt(22)
	v_add_co_u32_e32 v14, vcc, s6, v2
	v_and_b32_e32 v142, 64, v140
	s_nop 0
	v_addc_co_u32_e32 v15, vcc, 0, v3, vcc
	v_add_co_u32_e32 v16, vcc, s6, v4
	v_mad_u64_u32 v[130:131], s[6:7], v18, s36, v[0:1]
	s_nop 0
	v_addc_co_u32_e32 v17, vcc, 0, v5, vcc
	global_load_dwordx4 v[66:69], v[2:3], off
	global_load_dwordx4 v[74:77], v[4:5], off
	global_load_dwordx4 v[82:85], v[6:7], off
	global_load_dwordx4 v[90:93], v[8:9], off
	global_load_dwordx4 v[98:101], v[10:11], off
	global_load_dwordx4 v[106:109], v[12:13], off
	global_load_dwordx4 v[114:117], v[14:15], off
	global_load_dwordx4 v[122:125], v[16:17], off
	global_load_dwordx4 v[70:73], v[2:3], off offset:128
	global_load_dwordx4 v[78:81], v[4:5], off offset:128
	global_load_dwordx4 v[86:89], v[6:7], off offset:128
	global_load_dwordx4 v[94:97], v[8:9], off offset:128
	global_load_dwordx4 v[102:105], v[10:11], off offset:128
	global_load_dwordx4 v[110:113], v[12:13], off offset:128
	global_load_dwordx4 v[118:121], v[14:15], off offset:128
	global_load_dwordx4 v[126:129], v[16:17], off offset:128
	v_ashrrev_i32_e32 v2, 1, v140
	v_readlane_b32 s6, v254, 0
	v_and_b32_e32 v141, 0xffffffc0, v2
	v_add_u32_e32 v2, s20, v18
	v_readlane_b32 s7, v254, 1
	v_subrev_u32_e32 v4, s1, v2
	v_and_b32_e32 v0, 7, v140
	v_mov_b64_e32 v[2:3], s[6:7]
	v_mad_i64_i32 v[132:133], s[6:7], v4, s10, v[2:3]
	v_mad_i64_i32 v[134:135], s[6:7], v19, s10, v[2:3]
	v_mov_b32_e32 v2, 0
	v_lshlrev_b32_e32 v0, 4, v0
	s_mov_b32 s1, -2
	v_mov_b32_e32 v3, v2
	v_mov_b32_e32 v4, v2
	v_mov_b32_e32 v5, v2
	v_mov_b32_e32 v6, v2
	v_mov_b32_e32 v7, v2
	v_mov_b32_e32 v8, v2
	v_mov_b32_e32 v9, v2
	v_mov_b32_e32 v10, v2
	v_mov_b32_e32 v11, v2
	v_mov_b32_e32 v12, v2
	v_mov_b32_e32 v13, v2
	v_mov_b32_e32 v14, v2
	v_mov_b32_e32 v15, v2
	v_mov_b32_e32 v16, v2
	v_mov_b32_e32 v17, v2
	v_mov_b32_e32 v18, v2
	v_mov_b32_e32 v19, v2
	v_mov_b32_e32 v20, v2
	v_mov_b32_e32 v21, v2
	s_waitcnt vmcnt(37)
	v_mov_b32_e32 v22, v2
	v_mov_b32_e32 v23, v2
	v_mov_b32_e32 v24, v2
	v_mov_b32_e32 v25, v2
	v_mov_b32_e32 v26, v2
	v_mov_b32_e32 v27, v2
	v_mov_b32_e32 v28, v2
	v_mov_b32_e32 v29, v2
	s_waitcnt vmcnt(36)
	v_mov_b32_e32 v30, v2
	v_mov_b32_e32 v31, v2
	v_mov_b32_e32 v32, v2
	v_mov_b32_e32 v33, v2
	v_mov_b32_e32 v34, v2
	v_mov_b32_e32 v35, v2
	v_mov_b32_e32 v36, v2
	v_mov_b32_e32 v37, v2
	s_waitcnt vmcnt(35)
	v_mov_b32_e32 v38, v2
	v_mov_b32_e32 v39, v2
	v_mov_b32_e32 v40, v2
	v_mov_b32_e32 v41, v2
	v_mov_b32_e32 v42, v2
	v_mov_b32_e32 v43, v2
	v_mov_b32_e32 v44, v2
	v_mov_b32_e32 v45, v2
	s_waitcnt vmcnt(34)
	v_mov_b32_e32 v46, v2
	v_mov_b32_e32 v47, v2
	v_mov_b32_e32 v48, v2
	v_mov_b32_e32 v49, v2
	v_mov_b32_e32 v50, v2
	v_mov_b32_e32 v51, v2
	v_mov_b32_e32 v52, v2
	v_mov_b32_e32 v53, v2
	s_waitcnt vmcnt(33)
	v_mov_b32_e32 v54, v2
	v_mov_b32_e32 v55, v2
	v_mov_b32_e32 v56, v2
	v_mov_b32_e32 v57, v2
	v_mov_b32_e32 v58, v2
	v_mov_b32_e32 v59, v2
	v_mov_b32_e32 v60, v2
	v_mov_b32_e32 v61, v2
	s_waitcnt vmcnt(32)
	v_mov_b32_e32 v62, v2
	v_mov_b32_e32 v63, v2
	v_mov_b32_e32 v64, v2
	v_mov_b32_e32 v65, v2
	v_mov_b32_e32 v131, v195
	v_and_b32_e32 v143, 15, v131
	v_or_b32_e32 v144, v143, v142
	v_and_b32_e32 v148, 48, v131
	v_mul_u32_u24_e32 v131, 0x50, v144
	v_lshl_add_u32 v131, v131, 1, v148
	v_or_b32_e32 v143, v143, v141
	v_mad_u32_u24 v238, v143, s36, v148
	s_branch .LBB0_325
; DEV f32x4 mfma16(bf16x8 a, bf16x8 b, f32x4 c) { return __builtin_amdgcn_mfma_f32_16x16x32_bf16(a, b, c, 0, 0, 0); }
; #define G_LOAD(RA, RB, KT) { _Pragma("unroll") for (int i = 0; i < 4; i++) { \
;       RA[i] = *(const u32x4*)(Ap + (size_t)(i * 32) * lda + (KT) * 64); RB[i] = *(const u32x4*)(Bp + (size_t)(i * 32) * ldb + (KT) * 64); } }
; template <int TI, int TJ, int KS>
; DEV void mfma_lds(const bf16_t* Arows, int lda, const bf16_t* Brows, int ldb, int i0, int j0, f32x4 (&acc)[TI][TJ]) {
;     ...
;   for (int ks = 0; ks < KS; ks++) {
;     bf16x8 af[TI], bfr[TJ];
; #pragma unroll
;     for (int i = 0; i < TI; i++) af[i] = *(const bf16x8*)(Arows + (i0 + i * 16 + l15) * lda + ks * 32 + quad * 8);
; #pragma unroll
;     for (int j = 0; j < TJ; j++) bfr[j] = *(const bf16x8*)(Brows + (j0 + j * 16 + l15) * ldb + ks * 32 + quad * 8);
; #pragma unroll
;     for (int i = 0; i < TI; i++)
; #pragma unroll
;       for (int j = 0; j < TJ; j++) acc[i][j] = mfma16(af[i], bfr[j], acc[i][j]);
; template <class Epi>
; DEV void gemm_tile(const bf16_t* __restrict__ A, int lda, const bf16_t* __restrict__ Bt, int ldb, int K, int m0, int n0,
;                    Epi& epi, char* smem) {
;     ...
;     if (kt + 3 < nk) G_LOAD(ra1, rb1, kt + 3);
;     mfma_lds<4, 4, 2>(Bs, GLD, As, GLD, wn * 64, wm * 64, acc);
.LBB0_324:
	v_lshl_add_u64 v[132:133], v[132:133], 0, s[34:35]
	v_lshl_add_u64 v[134:135], v[134:135], 0, s[34:35]
	s_and_b64 vcc, exec, s[6:7]
	ds_read_b128 v[144:147], v131 offset:20480
	ds_read_b128 v[160:163], v238
	ds_read_b128 v[164:167], v238 offset:2560
	ds_read_b128 v[168:171], v238 offset:5120
	ds_read_b128 v[172:175], v238 offset:7680
	ds_read_b128 v[148:151], v131 offset:23040
	ds_read_b128 v[152:155], v131 offset:25600
	ds_read_b128 v[156:159], v131 offset:28160
	ds_read_b128 v[176:179], v238 offset:64
	ds_read_b128 v[180:183], v238 offset:2624
	s_waitcnt lgkmcnt(8)
	v_mfma_f32_16x16x32_bf16 v[62:65], v[144:147], v[160:163], v[62:65]
	s_waitcnt lgkmcnt(7)
	v_mfma_f32_16x16x32_bf16 v[58:61], v[144:147], v[164:167], v[58:61]
	s_waitcnt lgkmcnt(6)
	v_mfma_f32_16x16x32_bf16 v[54:57], v[144:147], v[168:171], v[54:57]
	s_waitcnt lgkmcnt(5)
	v_mfma_f32_16x16x32_bf16 v[50:53], v[144:147], v[172:175], v[50:53]
	ds_read_b128 v[144:147], v131 offset:20544
	s_waitcnt lgkmcnt(5)
	v_mfma_f32_16x16x32_bf16 v[46:49], v[148:151], v[160:163], v[46:49]
	v_mfma_f32_16x16x32_bf16 v[42:45], v[148:151], v[164:167], v[42:45]
	v_mfma_f32_16x16x32_bf16 v[38:41], v[148:151], v[168:171], v[38:41]
	v_mfma_f32_16x16x32_bf16 v[34:37], v[148:151], v[172:175], v[34:37]
	ds_read_b128 v[148:151], v131 offset:23104
	s_waitcnt lgkmcnt(5)
	v_mfma_f32_16x16x32_bf16 v[30:33], v[152:155], v[160:163], v[30:33]
	v_mfma_f32_16x16x32_bf16 v[26:29], v[152:155], v[164:167], v[26:29]
	v_mfma_f32_16x16x32_bf16 v[22:25], v[152:155], v[168:171], v[22:25]
	v_mfma_f32_16x16x32_bf16 v[18:21], v[152:155], v[172:175], v[18:21]
	ds_read_b128 v[152:155], v131 offset:25664
	s_waitcnt lgkmcnt(5)
	v_mfma_f32_16x16x32_bf16 v[6:9], v[156:159], v[168:171], v[6:9]
	v_mfma_f32_16x16x32_bf16 v[2:5], v[156:159], v[172:175], v[2:5]
	ds_read_b128 v[168:171], v238 offset:5184
	ds_read_b128 v[172:175], v238 offset:7744
	v_mfma_f32_16x16x32_bf16 v[14:17], v[156:159], v[160:163], v[14:17]
	v_mfma_f32_16x16x32_bf16 v[10:13], v[156:159], v[164:167], v[10:13]
	ds_read_b128 v[156:159], v131 offset:28224
	s_waitcnt lgkmcnt(5)
	v_mfma_f32_16x16x32_bf16 v[62:65], v[144:147], v[176:179], v[62:65]
	s_waitcnt lgkmcnt(4)
	v_mfma_f32_16x16x32_bf16 v[46:49], v[148:151], v[176:179], v[46:49]
	s_waitcnt lgkmcnt(3)
	v_mfma_f32_16x16x32_bf16 v[30:33], v[152:155], v[176:179], v[30:33]
	v_mfma_f32_16x16x32_bf16 v[58:61], v[144:147], v[180:183], v[58:61]
	v_mfma_f32_16x16x32_bf16 v[42:45], v[148:151], v[180:183], v[42:45]
	v_mfma_f32_16x16x32_bf16 v[26:29], v[152:155], v[180:183], v[26:29]
	s_waitcnt lgkmcnt(2)
	v_mfma_f32_16x16x32_bf16 v[54:57], v[144:147], v[168:171], v[54:57]
	v_mfma_f32_16x16x32_bf16 v[38:41], v[148:151], v[168:171], v[38:41]
	v_mfma_f32_16x16x32_bf16 v[22:25], v[152:155], v[168:171], v[22:25]
	s_waitcnt lgkmcnt(1)
	v_mfma_f32_16x16x32_bf16 v[50:53], v[144:147], v[172:175], v[50:53]
	v_mfma_f32_16x16x32_bf16 v[34:37], v[148:151], v[172:175], v[34:37]
	v_mfma_f32_16x16x32_bf16 v[18:21], v[152:155], v[172:175], v[18:21]
	s_waitcnt lgkmcnt(0)
	v_mfma_f32_16x16x32_bf16 v[14:17], v[156:159], v[176:179], v[14:17]
	v_mfma_f32_16x16x32_bf16 v[10:13], v[156:159], v[180:183], v[10:13]
	v_mfma_f32_16x16x32_bf16 v[6:9], v[156:159], v[168:171], v[6:9]
	v_mfma_f32_16x16x32_bf16 v[2:5], v[156:159], v[172:175], v[2:5]
	s_cbranch_vccnz .LBB0_329

; DEV f32x4 mfma16(bf16x8 a, bf16x8 b, f32x4 c) { return __builtin_amdgcn_mfma_f32_16x16x32_bf16(a, b, c, 0, 0, 0); }
; #define G_LOAD(RA, RB, KT) { _Pragma("unroll") for (int i = 0; i < 4; i++) { \
;       RA[i] = *(const u32x4*)(Ap + (size_t)(i * 32) * lda + (KT) * 64); RB[i] = *(const u32x4*)(Bp + (size_t)(i * 32) * ldb + (KT) * 64); } }
; #define G_STORE(RA, RB) { _Pragma("unroll") for (int i = 0; i < 4; i++) { \
;       *(u32x4*)(As + (lrow + i * 32) * GLD + lcc * 8) = RA[i]; *(u32x4*)(Bs + (lrow + i * 32) * GLD + lcc * 8) = RB[i]; } }
; template <int TI, int TJ, int KS>
; DEV void mfma_lds(const bf16_t* Arows, int lda, const bf16_t* Brows, int ldb, int i0, int j0, f32x4 (&acc)[TI][TJ]) {
;     ...
;   for (int ks = 0; ks < KS; ks++) {
;     bf16x8 af[TI], bfr[TJ];
; #pragma unroll
;     for (int i = 0; i < TI; i++) af[i] = *(const bf16x8*)(Arows + (i0 + i * 16 + l15) * lda + ks * 32 + quad * 8);
; #pragma unroll
;     for (int j = 0; j < TJ; j++) bfr[j] = *(const bf16x8*)(Brows + (j0 + j * 16 + l15) * ldb + ks * 32 + quad * 8);
; #pragma unroll
;     for (int i = 0; i < TI; i++)
; #pragma unroll
;       for (int j = 0; j < TJ; j++) acc[i][j] = mfma16(af[i], bfr[j], acc[i][j]);
; template <class Epi>
; DEV void gemm_tile(const bf16_t* __restrict__ A, int lda, const bf16_t* __restrict__ Bt, int ldb, int K, int m0, int n0,
;                    Epi& epi, char* smem) {
;     ...
;     mfma_lds<4, 4, 2>(Bs, GLD, As, GLD, wn * 64, wm * 64, acc);
;     __syncthreads();
;     G_STORE(ra1, rb1);
;     __syncthreads();
;     if (kt + 3 < nk) G_LOAD(ra1, rb1, kt + 3);
.LBB0_327:
	s_cmp_gt_u32 s1, 12
	ds_read_b128 v[144:147], v131 offset:20480
	ds_read_b128 v[160:163], v238
	ds_read_b128 v[164:167], v238 offset:2560
	ds_read_b128 v[168:171], v238 offset:5120
	ds_read_b128 v[172:175], v238 offset:7680
	ds_read_b128 v[148:151], v131 offset:23040
	ds_read_b128 v[152:155], v131 offset:25600
	ds_read_b128 v[156:159], v131 offset:28160
	ds_read_b128 v[176:179], v238 offset:64
	ds_read_b128 v[180:183], v238 offset:2624
	s_waitcnt lgkmcnt(8)
	v_mfma_f32_16x16x32_bf16 v[62:65], v[144:147], v[160:163], v[62:65]
	s_waitcnt lgkmcnt(7)
	v_mfma_f32_16x16x32_bf16 v[58:61], v[144:147], v[164:167], v[58:61]
	s_waitcnt lgkmcnt(6)
	v_mfma_f32_16x16x32_bf16 v[54:57], v[144:147], v[168:171], v[54:57]
	s_waitcnt lgkmcnt(5)
	v_mfma_f32_16x16x32_bf16 v[50:53], v[144:147], v[172:175], v[50:53]
	ds_read_b128 v[144:147], v131 offset:20544
	s_waitcnt lgkmcnt(5)
	v_mfma_f32_16x16x32_bf16 v[46:49], v[148:151], v[160:163], v[46:49]
	v_mfma_f32_16x16x32_bf16 v[42:45], v[148:151], v[164:167], v[42:45]
	v_mfma_f32_16x16x32_bf16 v[38:41], v[148:151], v[168:171], v[38:41]
	v_mfma_f32_16x16x32_bf16 v[34:37], v[148:151], v[172:175], v[34:37]
	ds_read_b128 v[148:151], v131 offset:23104
	s_waitcnt lgkmcnt(5)
	v_mfma_f32_16x16x32_bf16 v[30:33], v[152:155], v[160:163], v[30:33]
	v_mfma_f32_16x16x32_bf16 v[26:29], v[152:155], v[164:167], v[26:29]
	v_mfma_f32_16x16x32_bf16 v[22:25], v[152:155], v[168:171], v[22:25]
	v_mfma_f32_16x16x32_bf16 v[18:21], v[152:155], v[172:175], v[18:21]
	ds_read_b128 v[152:155], v131 offset:25664
	s_waitcnt lgkmcnt(5)
	v_mfma_f32_16x16x32_bf16 v[6:9], v[156:159], v[168:171], v[6:9]
	v_mfma_f32_16x16x32_bf16 v[2:5], v[156:159], v[172:175], v[2:5]
	ds_read_b128 v[168:171], v238 offset:5184
	ds_read_b128 v[172:175], v238 offset:7744
	v_mfma_f32_16x16x32_bf16 v[14:17], v[156:159], v[160:163], v[14:17]
	v_mfma_f32_16x16x32_bf16 v[10:13], v[156:159], v[164:167], v[10:13]
	ds_read_b128 v[156:159], v131 offset:28224
	s_waitcnt lgkmcnt(5)
	v_mfma_f32_16x16x32_bf16 v[62:65], v[144:147], v[176:179], v[62:65]
	s_waitcnt lgkmcnt(4)
	v_mfma_f32_16x16x32_bf16 v[46:49], v[148:151], v[176:179], v[46:49]
	s_waitcnt lgkmcnt(3)
	v_mfma_f32_16x16x32_bf16 v[30:33], v[152:155], v[176:179], v[30:33]
	v_mfma_f32_16x16x32_bf16 v[58:61], v[144:147], v[180:183], v[58:61]
	v_mfma_f32_16x16x32_bf16 v[42:45], v[148:151], v[180:183], v[42:45]
	v_mfma_f32_16x16x32_bf16 v[26:29], v[152:155], v[180:183], v[26:29]
	s_waitcnt lgkmcnt(2)
	v_mfma_f32_16x16x32_bf16 v[54:57], v[144:147], v[168:171], v[54:57]
	v_mfma_f32_16x16x32_bf16 v[38:41], v[148:151], v[168:171], v[38:41]
	v_mfma_f32_16x16x32_bf16 v[22:25], v[152:155], v[168:171], v[22:25]
	s_waitcnt lgkmcnt(1)
	v_mfma_f32_16x16x32_bf16 v[50:53], v[144:147], v[172:175], v[50:53]
	v_mfma_f32_16x16x32_bf16 v[34:37], v[148:151], v[172:175], v[34:37]
	v_mfma_f32_16x16x32_bf16 v[18:21], v[152:155], v[172:175], v[18:21]
	s_waitcnt lgkmcnt(0)
	v_mfma_f32_16x16x32_bf16 v[14:17], v[156:159], v[176:179], v[14:17]
	s_barrier
	v_mfma_f32_16x16x32_bf16 v[10:13], v[156:159], v[180:183], v[10:13]
	s_waitcnt vmcnt(8)
	ds_write_b128 v130, v[70:73]
	ds_write_b128 v130, v[78:81] offset:20480
	ds_write_b128 v130, v[86:89] offset:5120
	ds_write_b128 v130, v[94:97] offset:25600
	ds_write_b128 v130, v[102:105] offset:10240
	ds_write_b128 v130, v[110:113] offset:30720
	ds_write_b128 v130, v[118:121] offset:15360
	ds_write_b128 v130, v[126:129] offset:35840
	v_mfma_f32_16x16x32_bf16 v[6:9], v[156:159], v[168:171], v[6:9]
	s_waitcnt lgkmcnt(0)
	s_barrier
	v_mfma_f32_16x16x32_bf16 v[2:5], v[156:159], v[172:175], v[2:5]
	s_cbranch_scc1 .LBB0_324
	v_add_co_u32_e32 v70, vcc, 0x4200000, v138
	s_nop 1
	v_addc_co_u32_e32 v71, vcc, 0, v139, vcc
	v_add_co_u32_e32 v78, vcc, 0xa900000, v136
	global_load_dwordx4 v[70:73], v[70:71], off offset:384
	s_nop 0
	v_addc_co_u32_e32 v79, vcc, 0, v137, vcc
	v_add_co_u32_e32 v86, vcc, 0x4211000, v138
	global_load_dwordx4 v[78:81], v[78:79], off offset:384
	s_nop 0
	v_addc_co_u32_e32 v87, vcc, 0, v139, vcc
	v_add_co_u32_e32 v94, vcc, 0xa911000, v136
	global_load_dwordx4 v[86:89], v[86:87], off offset:384
	s_nop 0
	v_addc_co_u32_e32 v95, vcc, 0, v137, vcc
	v_add_co_u32_e32 v102, vcc, 0x4222000, v138
	global_load_dwordx4 v[94:97], v[94:95], off offset:384
	s_nop 0
	v_addc_co_u32_e32 v103, vcc, 0, v139, vcc
	v_add_co_u32_e32 v110, vcc, 0xa922000, v136
	global_load_dwordx4 v[102:105], v[102:103], off offset:384
	s_nop 0
	v_addc_co_u32_e32 v111, vcc, 0, v137, vcc
	v_add_co_u32_e32 v118, vcc, 0x4233000, v138
	global_load_dwordx4 v[110:113], v[110:111], off offset:384
	s_nop 0
	v_addc_co_u32_e32 v119, vcc, 0, v139, vcc
	v_add_co_u32_e32 v126, vcc, 0xa933000, v136
	global_load_dwordx4 v[118:121], v[118:119], off offset:384
	s_nop 0
	v_addc_co_u32_e32 v127, vcc, 0, v137, vcc
	global_load_dwordx4 v[126:129], v[126:127], off offset:384
	s_branch .LBB0_324

; DEV int tidx() { int t = threadIdx.x; asm volatile("" : "+v"(t)); return t; }
; #define G_LOAD(RA, RB, KT) { _Pragma("unroll") for (int i = 0; i < 4; i++) { \
;       RA[i] = *(const u32x4*)(Ap + (size_t)(i * 32) * lda + (KT) * 64); RB[i] = *(const u32x4*)(Bp + (size_t)(i * 32) * ldb + (KT) * 64); } }
; template <class Epi>
; DEV void gemm_tile(const bf16_t* __restrict__ A, int lda, const bf16_t* __restrict__ Bt, int ldb, int K, int m0, int n0,
;                    Epi& epi, char* smem) {
;     ...
;   const int tid = tidx(), lane = tid & 63, w = tid >> 6, wm = w >> 1, wn = w & 1;
;   const int l15 = lane & 15, quad = lane >> 4;
;   f32x4 acc[4][4];
; #pragma unroll
;   for (int i = 0; i < 4; i++)
; #pragma unroll
;     for (int j = 0; j < 4; j++) acc[i][j] = (f32x4){0.f, 0.f, 0.f, 0.f};
;   u32x4 ra0[4], rb0[4], ra1[4], rb1[4];
;   const int nk = K >> 6;
;   const int lrow = tid >> 3, lcc = tid & 7;
;   const bf16_t* Ap = A + (size_t)(m0 + lrow) * lda + lcc * 8;
;   const bf16_t* Bp = Bt + (size_t)(n0 + lrow) * ldb + lcc * 8;
;     ...
;   G_LOAD(ra0, rb0, 0);
;   G_LOAD(ra1, rb1, 1);
.LBB0_644:
	s_ashr_i32 s9, s11, 6
	s_and_b32 s8, s11, 7
	s_and_b32 s12, s9, -8
	s_or_b32 s12, s12, s8
	s_lshr_b32 s8, s11, 31
	s_add_i32 s8, s12, s8
	s_ashr_i32 s8, s8, 1
	s_lshl_b32 s13, s8, 3
	s_bfe_u32 s14, s11, 0x30006
	s_or_b32 s13, s13, s14
	s_cmpk_gt_i32 s13, 0x83
	s_cbranch_scc1 .LBB0_643
	v_mov_b32_e32 v145, v195
	s_lshr_b32 s14, s11, 6
	s_lshl_b32 s12, s12, 3
	s_lshl_b32 s18, s8, 4
	s_lshl_b32 s13, s13, 7
	s_and_b32 s15, s10, 7
	v_ashrrev_i32_e32 v66, 3, v145
	s_and_b32 s14, s14, 7
	s_sub_i32 s12, s12, s18
	s_movk_i32 s20, 0x880
	s_bfe_u32 s19, s11, 0x30003
	v_add_u32_e32 v0, s13, v66
	v_mov_b64_e32 v[2:3], s[6:7]
	s_lshl_b32 s16, s15, 3
	s_lshl_b32 s17, s14, 7
	s_or_b32 s12, s12, s19
	v_mad_i64_i32 v[2:3], s[14:15], v0, s20, v[2:3]
	v_lshlrev_b32_e32 v0, 4, v145
	s_lshl_b32 s12, s12, 7
	v_and_b32_e32 v0, 0x70, v0
	v_lshl_add_u64 v[6:7], v[2:3], 0, v[0:1]
	v_add_u32_e32 v4, s12, v66
	v_mov_b64_e32 v[2:3], s[2:3]
	v_mad_i64_i32 v[2:3], s[14:15], v4, s20, v[2:3]
	s_mov_b32 s14, 0x11000
	s_waitcnt vmcnt(21)
	v_add_co_u32_e32 v22, vcc, s14, v6
	v_lshl_add_u64 v[14:15], v[2:3], 0, v[0:1]
	s_nop 0
	v_addc_co_u32_e32 v23, vcc, 0, v7, vcc
	s_waitcnt vmcnt(20)
	v_add_co_u32_e32 v30, vcc, s14, v14
	s_mov_b32 s14, 0x22000
	s_nop 0
	v_addc_co_u32_e32 v31, vcc, 0, v15, vcc
	s_waitcnt vmcnt(19)
	v_add_co_u32_e32 v38, vcc, s14, v6
	s_lshl_b32 s9, s9, 3
	s_nop 0
	v_addc_co_u32_e32 v39, vcc, 0, v7, vcc
	s_waitcnt vmcnt(18)
	v_add_co_u32_e32 v46, vcc, s14, v14
	s_mov_b32 s14, 0x33000
	s_nop 0
	v_addc_co_u32_e32 v47, vcc, 0, v15, vcc
	s_waitcnt vmcnt(17)
	v_add_co_u32_e32 v54, vcc, s14, v6
	s_and_b32 s9, s9, 0x1ffffc0
	s_nop 0
	v_addc_co_u32_e32 v55, vcc, 0, v7, vcc
	s_waitcnt vmcnt(16)
	v_add_co_u32_e32 v62, vcc, s14, v14
	s_or_b32 s9, s9, s16
	s_nop 0
	v_addc_co_u32_e32 v63, vcc, 0, v15, vcc
	global_load_dwordx4 v[2:5], v[6:7], off
	s_nop 0
	global_load_dwordx4 v[10:13], v[14:15], off
	s_nop 0
	global_load_dwordx4 v[18:21], v[22:23], off
	s_nop 0
	global_load_dwordx4 v[26:29], v[30:31], off
	s_nop 0
	global_load_dwordx4 v[34:37], v[38:39], off
	s_nop 0
	global_load_dwordx4 v[42:45], v[46:47], off
	s_nop 0
	global_load_dwordx4 v[50:53], v[54:55], off
	s_nop 0
	global_load_dwordx4 v[58:61], v[62:63], off
	s_nop 0
	global_load_dwordx4 v[6:9], v[6:7], off offset:128
	s_nop 0
	global_load_dwordx4 v[14:17], v[14:15], off offset:128
	s_nop 0
	global_load_dwordx4 v[22:25], v[22:23], off offset:128
	s_nop 0
	global_load_dwordx4 v[30:33], v[30:31], off offset:128
	s_nop 0
	global_load_dwordx4 v[38:41], v[38:39], off offset:128
	s_nop 0
	global_load_dwordx4 v[46:49], v[46:47], off offset:128
	s_nop 0
	global_load_dwordx4 v[54:57], v[54:55], off offset:128
	s_nop 0
	global_load_dwordx4 v[62:65], v[62:63], off offset:128
	s_or_b32 s9, s9, s19
	v_mad_u64_u32 v[134:135], s[14:15], v66, s36, v[0:1]
	s_sub_i32 s9, s9, s18
	v_ashrrev_i32_e32 v67, 1, v145
	s_lshl_b32 s14, s9, 7
	v_and_b32_e32 v146, 0xffffffc0, v67
	v_ashrrev_i32_e32 v67, 31, v66
	s_ashr_i32 s15, s14, 31
	s_lshl_b32 s8, s8, 10
	s_movk_i32 s19, 0x880
	v_lshl_add_u64 v[68:69], v[66:67], 0, s[14:15]
	v_mov_b64_e32 v[70:71], s[28:29]
	s_or_b32 s8, s17, s8
	v_and_b32_e32 v0, 7, v145
	v_mad_u64_u32 v[136:137], s[14:15], v68, s19, v[70:71]
	v_add_u32_e32 v66, s8, v66
	v_mov_b32_e32 v118, 0
	v_and_b32_e32 v144, 64, v145
	v_lshlrev_b32_e32 v0, 4, v0
	v_mad_i32_i24 v137, v69, s19, v137
	v_mad_i64_i32 v[138:139], s[8:9], v66, s19, v[70:71]
	s_mov_b32 s14, -2
	v_mov_b32_e32 v119, v118
	v_mov_b32_e32 v120, v118
	v_mov_b32_e32 v121, v118
	v_mov_b32_e32 v126, v118
	v_mov_b32_e32 v127, v118
	v_mov_b32_e32 v128, v118
	v_mov_b32_e32 v129, v118
	v_mov_b32_e32 v90, v118
	v_mov_b32_e32 v91, v118
	v_mov_b32_e32 v92, v118
	v_mov_b32_e32 v93, v118
	v_mov_b32_e32 v98, v118
	v_mov_b32_e32 v99, v118
	v_mov_b32_e32 v100, v118
	v_mov_b32_e32 v101, v118
	v_mov_b32_e32 v66, v118
	v_mov_b32_e32 v67, v118
	v_mov_b32_e32 v68, v118
	v_mov_b32_e32 v69, v118
	v_mov_b32_e32 v70, v118
	v_mov_b32_e32 v71, v118
	v_mov_b32_e32 v72, v118
	v_mov_b32_e32 v73, v118
	v_mov_b32_e32 v74, v118
	v_mov_b32_e32 v75, v118
	v_mov_b32_e32 v76, v118
	v_mov_b32_e32 v77, v118
	v_mov_b32_e32 v82, v118
	v_mov_b32_e32 v83, v118
	v_mov_b32_e32 v84, v118
	v_mov_b32_e32 v85, v118
	v_mov_b32_e32 v78, v118
	v_mov_b32_e32 v79, v118
	v_mov_b32_e32 v80, v118
	v_mov_b32_e32 v81, v118
	v_mov_b32_e32 v86, v118
	v_mov_b32_e32 v87, v118
	v_mov_b32_e32 v88, v118
	v_mov_b32_e32 v89, v118
	v_mov_b32_e32 v94, v118
	v_mov_b32_e32 v95, v118
	v_mov_b32_e32 v96, v118
	v_mov_b32_e32 v97, v118
	v_mov_b32_e32 v102, v118
	v_mov_b32_e32 v103, v118
	v_mov_b32_e32 v104, v118
	v_mov_b32_e32 v105, v118
	v_mov_b32_e32 v110, v118
	v_mov_b32_e32 v111, v118
	v_mov_b32_e32 v112, v118
	v_mov_b32_e32 v113, v118
	v_mov_b32_e32 v114, v118
	v_mov_b32_e32 v115, v118
	v_mov_b32_e32 v116, v118
	v_mov_b32_e32 v117, v118
	v_mov_b32_e32 v122, v118
	v_mov_b32_e32 v123, v118
	v_mov_b32_e32 v124, v118
	v_mov_b32_e32 v125, v118
	v_mov_b32_e32 v106, v118
	v_mov_b32_e32 v107, v118
	v_mov_b32_e32 v108, v118
	v_mov_b32_e32 v109, v118
	v_mov_b32_e32 v130, v195
	v_and_b32_e32 v135, 15, v130
	v_or_b32_e32 v131, v135, v144
	v_and_b32_e32 v148, 48, v130
	v_mul_u32_u24_e32 v130, 0x50, v131
	v_lshl_add_u32 v147, v130, 1, v148
	v_or_b32_e32 v135, v135, v146
	v_mad_u32_u24 v238, v135, s36, v148
	s_branch .LBB0_647
; DEV f32x4 mfma16(bf16x8 a, bf16x8 b, f32x4 c) { return __builtin_amdgcn_mfma_f32_16x16x32_bf16(a, b, c, 0, 0, 0); }
; #define G_LOAD(RA, RB, KT) { _Pragma("unroll") for (int i = 0; i < 4; i++) { \
;       RA[i] = *(const u32x4*)(Ap + (size_t)(i * 32) * lda + (KT) * 64); RB[i] = *(const u32x4*)(Bp + (size_t)(i * 32) * ldb + (KT) * 64); } }
; template <int TI, int TJ, int KS>
; DEV void mfma_lds(const bf16_t* Arows, int lda, const bf16_t* Brows, int ldb, int i0, int j0, f32x4 (&acc)[TI][TJ]) {
;     ...
;   for (int ks = 0; ks < KS; ks++) {
;     bf16x8 af[TI], bfr[TJ];
; #pragma unroll
;     for (int i = 0; i < TI; i++) af[i] = *(const bf16x8*)(Arows + (i0 + i * 16 + l15) * lda + ks * 32 + quad * 8);
; #pragma unroll
;     for (int j = 0; j < TJ; j++) bfr[j] = *(const bf16x8*)(Brows + (j0 + j * 16 + l15) * ldb + ks * 32 + quad * 8);
; #pragma unroll
;     for (int i = 0; i < TI; i++)
; #pragma unroll
;       for (int j = 0; j < TJ; j++) acc[i][j] = mfma16(af[i], bfr[j], acc[i][j]);
; template <class Epi>
; DEV void gemm_tile(const bf16_t* __restrict__ A, int lda, const bf16_t* __restrict__ Bt, int ldb, int K, int m0, int n0,
;                    Epi& epi, char* smem) {
;     ...
;     if (kt + 3 < nk) G_LOAD(ra1, rb1, kt + 3);
;     mfma_lds<4, 4, 2>(Bs, GLD, As, GLD, wn * 64, wm * 64, acc);
.LBB0_646:
	v_lshl_add_u64 v[136:137], v[136:137], 0, s[34:35]
	v_lshl_add_u64 v[138:139], v[138:139], 0, s[34:35]
	s_andn2_b64 vcc, exec, s[8:9]
	ds_read_b128 v[148:151], v147 offset:20480
	ds_read_b128 v[164:167], v238
	ds_read_b128 v[168:171], v238 offset:2560
	ds_read_b128 v[172:175], v238 offset:5120
	ds_read_b128 v[176:179], v238 offset:7680
	ds_read_b128 v[152:155], v147 offset:23040
	ds_read_b128 v[156:159], v147 offset:25600
	ds_read_b128 v[160:163], v147 offset:28160
	ds_read_b128 v[180:183], v238 offset:64
	ds_read_b128 v[184:187], v238 offset:2624
	s_waitcnt lgkmcnt(8)
	v_mfma_f32_16x16x32_bf16 v[106:109], v[148:151], v[164:167], v[106:109]
	s_waitcnt lgkmcnt(7)
	v_mfma_f32_16x16x32_bf16 v[122:125], v[148:151], v[168:171], v[122:125]
	s_waitcnt lgkmcnt(6)
	v_mfma_f32_16x16x32_bf16 v[114:117], v[148:151], v[172:175], v[114:117]
	s_waitcnt lgkmcnt(5)
	v_mfma_f32_16x16x32_bf16 v[110:113], v[148:151], v[176:179], v[110:113]
	ds_read_b128 v[148:151], v147 offset:20544
	s_waitcnt lgkmcnt(5)
	v_mfma_f32_16x16x32_bf16 v[102:105], v[152:155], v[164:167], v[102:105]
	v_mfma_f32_16x16x32_bf16 v[94:97], v[152:155], v[168:171], v[94:97]
	v_mfma_f32_16x16x32_bf16 v[86:89], v[152:155], v[172:175], v[86:89]
	v_mfma_f32_16x16x32_bf16 v[78:81], v[152:155], v[176:179], v[78:81]
	ds_read_b128 v[152:155], v147 offset:23104
	s_waitcnt lgkmcnt(5)
	v_mfma_f32_16x16x32_bf16 v[82:85], v[156:159], v[164:167], v[82:85]
	v_mfma_f32_16x16x32_bf16 v[74:77], v[156:159], v[168:171], v[74:77]
	v_mfma_f32_16x16x32_bf16 v[70:73], v[156:159], v[172:175], v[70:73]
	v_mfma_f32_16x16x32_bf16 v[66:69], v[156:159], v[176:179], v[66:69]
	ds_read_b128 v[156:159], v147 offset:25664
	s_waitcnt lgkmcnt(5)
	v_mfma_f32_16x16x32_bf16 v[126:129], v[160:163], v[172:175], v[126:129]
	v_mfma_f32_16x16x32_bf16 v[118:121], v[160:163], v[176:179], v[118:121]
	ds_read_b128 v[172:175], v238 offset:5184
	ds_read_b128 v[176:179], v238 offset:7744
	v_mfma_f32_16x16x32_bf16 v[98:101], v[160:163], v[164:167], v[98:101]
	v_mfma_f32_16x16x32_bf16 v[90:93], v[160:163], v[168:171], v[90:93]
	ds_read_b128 v[160:163], v147 offset:28224
	s_waitcnt lgkmcnt(5)
	v_mfma_f32_16x16x32_bf16 v[106:109], v[148:151], v[180:183], v[106:109]
	s_waitcnt lgkmcnt(4)
	v_mfma_f32_16x16x32_bf16 v[102:105], v[152:155], v[180:183], v[102:105]
	s_waitcnt lgkmcnt(3)
	v_mfma_f32_16x16x32_bf16 v[82:85], v[156:159], v[180:183], v[82:85]
	v_mfma_f32_16x16x32_bf16 v[122:125], v[148:151], v[184:187], v[122:125]
	v_mfma_f32_16x16x32_bf16 v[94:97], v[152:155], v[184:187], v[94:97]
	v_mfma_f32_16x16x32_bf16 v[74:77], v[156:159], v[184:187], v[74:77]
	s_waitcnt lgkmcnt(2)
	v_mfma_f32_16x16x32_bf16 v[114:117], v[148:151], v[172:175], v[114:117]
	v_mfma_f32_16x16x32_bf16 v[86:89], v[152:155], v[172:175], v[86:89]
	v_mfma_f32_16x16x32_bf16 v[70:73], v[156:159], v[172:175], v[70:73]
	s_waitcnt lgkmcnt(1)
	v_mfma_f32_16x16x32_bf16 v[110:113], v[148:151], v[176:179], v[110:113]
	v_mfma_f32_16x16x32_bf16 v[78:81], v[152:155], v[176:179], v[78:81]
	v_mfma_f32_16x16x32_bf16 v[66:69], v[156:159], v[176:179], v[66:69]
	s_waitcnt lgkmcnt(0)
	v_mfma_f32_16x16x32_bf16 v[98:101], v[160:163], v[180:183], v[98:101]
	v_mfma_f32_16x16x32_bf16 v[90:93], v[160:163], v[184:187], v[90:93]
	v_mfma_f32_16x16x32_bf16 v[126:129], v[160:163], v[172:175], v[126:129]
	v_mfma_f32_16x16x32_bf16 v[118:121], v[160:163], v[176:179], v[118:121]
	s_cbranch_vccz .LBB0_642

; DEV f32x4 mfma16(bf16x8 a, bf16x8 b, f32x4 c) { return __builtin_amdgcn_mfma_f32_16x16x32_bf16(a, b, c, 0, 0, 0); }
; #define G_LOAD(RA, RB, KT) { _Pragma("unroll") for (int i = 0; i < 4; i++) { \
;       RA[i] = *(const u32x4*)(Ap + (size_t)(i * 32) * lda + (KT) * 64); RB[i] = *(const u32x4*)(Bp + (size_t)(i * 32) * ldb + (KT) * 64); } }
; #define G_STORE(RA, RB) { _Pragma("unroll") for (int i = 0; i < 4; i++) { \
;       *(u32x4*)(As + (lrow + i * 32) * GLD + lcc * 8) = RA[i]; *(u32x4*)(Bs + (lrow + i * 32) * GLD + lcc * 8) = RB[i]; } }
; template <int TI, int TJ, int KS>
; DEV void mfma_lds(const bf16_t* Arows, int lda, const bf16_t* Brows, int ldb, int i0, int j0, f32x4 (&acc)[TI][TJ]) {
;     ...
;   for (int ks = 0; ks < KS; ks++) {
;     bf16x8 af[TI], bfr[TJ];
; #pragma unroll
;     for (int i = 0; i < TI; i++) af[i] = *(const bf16x8*)(Arows + (i0 + i * 16 + l15) * lda + ks * 32 + quad * 8);
; #pragma unroll
;     for (int j = 0; j < TJ; j++) bfr[j] = *(const bf16x8*)(Brows + (j0 + j * 16 + l15) * ldb + ks * 32 + quad * 8);
; #pragma unroll
;     for (int i = 0; i < TI; i++)
; #pragma unroll
;       for (int j = 0; j < TJ; j++) acc[i][j] = mfma16(af[i], bfr[j], acc[i][j]);
; template <class Epi>
; DEV void gemm_tile(const bf16_t* __restrict__ A, int lda, const bf16_t* __restrict__ Bt, int ldb, int K, int m0, int n0,
;                    Epi& epi, char* smem) {
;     ...
;     mfma_lds<4, 4, 2>(Bs, GLD, As, GLD, wn * 64, wm * 64, acc);
;     __syncthreads();
;     G_STORE(ra1, rb1);
;     __syncthreads();
;     if (kt + 3 < nk) G_LOAD(ra1, rb1, kt + 3);
.LBB0_649:
	s_cmp_gt_u32 s14, 12
	ds_read_b128 v[148:151], v147 offset:20480
	ds_read_b128 v[164:167], v238
	ds_read_b128 v[168:171], v238 offset:2560
	ds_read_b128 v[172:175], v238 offset:5120
	ds_read_b128 v[176:179], v238 offset:7680
	ds_read_b128 v[152:155], v147 offset:23040
	ds_read_b128 v[156:159], v147 offset:25600
	ds_read_b128 v[160:163], v147 offset:28160
	ds_read_b128 v[180:183], v238 offset:64
	ds_read_b128 v[184:187], v238 offset:2624
	s_waitcnt lgkmcnt(8)
	v_mfma_f32_16x16x32_bf16 v[106:109], v[148:151], v[164:167], v[106:109]
	s_waitcnt lgkmcnt(7)
	v_mfma_f32_16x16x32_bf16 v[122:125], v[148:151], v[168:171], v[122:125]
	s_waitcnt lgkmcnt(6)
	v_mfma_f32_16x16x32_bf16 v[114:117], v[148:151], v[172:175], v[114:117]
	s_waitcnt lgkmcnt(5)
	v_mfma_f32_16x16x32_bf16 v[110:113], v[148:151], v[176:179], v[110:113]
	ds_read_b128 v[148:151], v147 offset:20544
	s_waitcnt lgkmcnt(5)
	v_mfma_f32_16x16x32_bf16 v[102:105], v[152:155], v[164:167], v[102:105]
	v_mfma_f32_16x16x32_bf16 v[94:97], v[152:155], v[168:171], v[94:97]
	v_mfma_f32_16x16x32_bf16 v[86:89], v[152:155], v[172:175], v[86:89]
	v_mfma_f32_16x16x32_bf16 v[78:81], v[152:155], v[176:179], v[78:81]
	ds_read_b128 v[152:155], v147 offset:23104
	s_waitcnt lgkmcnt(5)
	v_mfma_f32_16x16x32_bf16 v[82:85], v[156:159], v[164:167], v[82:85]
	v_mfma_f32_16x16x32_bf16 v[74:77], v[156:159], v[168:171], v[74:77]
	v_mfma_f32_16x16x32_bf16 v[70:73], v[156:159], v[172:175], v[70:73]
	v_mfma_f32_16x16x32_bf16 v[66:69], v[156:159], v[176:179], v[66:69]
	ds_read_b128 v[156:159], v147 offset:25664
	s_waitcnt lgkmcnt(5)
	v_mfma_f32_16x16x32_bf16 v[126:129], v[160:163], v[172:175], v[126:129]
	v_mfma_f32_16x16x32_bf16 v[118:121], v[160:163], v[176:179], v[118:121]
	ds_read_b128 v[172:175], v238 offset:5184
	ds_read_b128 v[176:179], v238 offset:7744
	v_mfma_f32_16x16x32_bf16 v[98:101], v[160:163], v[164:167], v[98:101]
	v_mfma_f32_16x16x32_bf16 v[90:93], v[160:163], v[168:171], v[90:93]
	ds_read_b128 v[160:163], v147 offset:28224
	s_waitcnt lgkmcnt(5)
	v_mfma_f32_16x16x32_bf16 v[106:109], v[148:151], v[180:183], v[106:109]
	s_waitcnt lgkmcnt(4)
	v_mfma_f32_16x16x32_bf16 v[102:105], v[152:155], v[180:183], v[102:105]
	s_waitcnt lgkmcnt(3)
	v_mfma_f32_16x16x32_bf16 v[82:85], v[156:159], v[180:183], v[82:85]
	v_mfma_f32_16x16x32_bf16 v[122:125], v[148:151], v[184:187], v[122:125]
	v_mfma_f32_16x16x32_bf16 v[94:97], v[152:155], v[184:187], v[94:97]
	v_mfma_f32_16x16x32_bf16 v[74:77], v[156:159], v[184:187], v[74:77]
	s_waitcnt lgkmcnt(2)
	v_mfma_f32_16x16x32_bf16 v[114:117], v[148:151], v[172:175], v[114:117]
	v_mfma_f32_16x16x32_bf16 v[86:89], v[152:155], v[172:175], v[86:89]
	v_mfma_f32_16x16x32_bf16 v[70:73], v[156:159], v[172:175], v[70:73]
	s_waitcnt lgkmcnt(1)
	v_mfma_f32_16x16x32_bf16 v[110:113], v[148:151], v[176:179], v[110:113]
	v_mfma_f32_16x16x32_bf16 v[78:81], v[152:155], v[176:179], v[78:81]
	v_mfma_f32_16x16x32_bf16 v[66:69], v[156:159], v[176:179], v[66:69]
	s_waitcnt lgkmcnt(0)
	v_mfma_f32_16x16x32_bf16 v[98:101], v[160:163], v[180:183], v[98:101]
	s_barrier
	v_mfma_f32_16x16x32_bf16 v[90:93], v[160:163], v[184:187], v[90:93]
	s_waitcnt vmcnt(8)
	ds_write_b128 v134, v[6:9]
	ds_write_b128 v134, v[14:17] offset:20480
	ds_write_b128 v134, v[22:25] offset:5120
	ds_write_b128 v134, v[30:33] offset:25600
	ds_write_b128 v134, v[38:41] offset:10240
	ds_write_b128 v134, v[46:49] offset:30720
	ds_write_b128 v134, v[54:57] offset:15360
	ds_write_b128 v134, v[62:65] offset:35840
	v_mfma_f32_16x16x32_bf16 v[126:129], v[160:163], v[172:175], v[126:129]
	s_waitcnt lgkmcnt(0)
	s_barrier
	v_mfma_f32_16x16x32_bf16 v[118:121], v[160:163], v[176:179], v[118:121]
	s_cbranch_scc1 .LBB0_646
	v_add_co_u32_e32 v6, vcc, 0x4200000, v142
	s_nop 1
	v_addc_co_u32_e32 v7, vcc, 0, v143, vcc
	v_add_co_u32_e32 v14, vcc, 0xb5c0000, v140
	global_load_dwordx4 v[6:9], v[6:7], off offset:384
	s_nop 0
	v_addc_co_u32_e32 v15, vcc, 0, v141, vcc
	v_add_co_u32_e32 v22, vcc, 0x4211000, v142
	global_load_dwordx4 v[14:17], v[14:15], off offset:384
	s_nop 0
	v_addc_co_u32_e32 v23, vcc, 0, v143, vcc
	v_add_co_u32_e32 v30, vcc, 0xb5d1000, v140
	global_load_dwordx4 v[22:25], v[22:23], off offset:384
	s_nop 0
	v_addc_co_u32_e32 v31, vcc, 0, v141, vcc
	v_add_co_u32_e32 v38, vcc, 0x4222000, v142
	global_load_dwordx4 v[30:33], v[30:31], off offset:384
	s_nop 0
	v_addc_co_u32_e32 v39, vcc, 0, v143, vcc
	v_add_co_u32_e32 v46, vcc, 0xb5e2000, v140
	global_load_dwordx4 v[38:41], v[38:39], off offset:384
	s_nop 0
	v_addc_co_u32_e32 v47, vcc, 0, v141, vcc
	v_add_co_u32_e32 v54, vcc, 0x4233000, v142
	global_load_dwordx4 v[46:49], v[46:47], off offset:384
	s_nop 0
	v_addc_co_u32_e32 v55, vcc, 0, v143, vcc
	v_add_co_u32_e32 v62, vcc, 0xb5f3000, v140
	global_load_dwordx4 v[54:57], v[54:55], off offset:384
	s_nop 0
	v_addc_co_u32_e32 v63, vcc, 0, v141, vcc
	global_load_dwordx4 v[62:65], v[62:63], off offset:384
	s_branch .LBB0_646

; DEV int tidx() { int t = threadIdx.x; asm volatile("" : "+v"(t)); return t; }
; #define G_LOAD(RA, RB, KT) { _Pragma("unroll") for (int i = 0; i < 4; i++) { \
;       RA[i] = *(const u32x4*)(Ap + (size_t)(i * 32) * lda + (KT) * 64); RB[i] = *(const u32x4*)(Bp + (size_t)(i * 32) * ldb + (KT) * 64); } }
; template <class Epi>
; DEV void gemm_tile(const bf16_t* __restrict__ A, int lda, const bf16_t* __restrict__ Bt, int ldb, int K, int m0, int n0,
;                    Epi& epi, char* smem) {
;     ...
;   const int tid = tidx(), lane = tid & 63, w = tid >> 6, wm = w >> 1, wn = w & 1;
;   const int l15 = lane & 15, quad = lane >> 4;
;   f32x4 acc[4][4];
; #pragma unroll
;   for (int i = 0; i < 4; i++)
; #pragma unroll
;     for (int j = 0; j < 4; j++) acc[i][j] = (f32x4){0.f, 0.f, 0.f, 0.f};
;   u32x4 ra0[4], rb0[4], ra1[4], rb1[4];
;   const int nk = K >> 6;
;   const int lrow = tid >> 3, lcc = tid & 7;
;   const bf16_t* Ap = A + (size_t)(m0 + lrow) * lda + lcc * 8;
;   const bf16_t* Bp = Bt + (size_t)(n0 + lrow) * ldb + lcc * 8;
;     ...
;   G_LOAD(ra0, rb0, 0);
;   G_LOAD(ra1, rb1, 1);
.LBB0_668:
	s_ashr_i32 s8, s12, 6
	s_and_b32 s9, s12, 7
	s_and_b32 s13, s8, 0x1ffffff8
	s_or_b32 s9, s13, s9
	s_lshl_b32 s9, s9, 3
	s_bfe_u32 s13, s12, 0x30006
	s_or_b32 s9, s9, s13
	s_cmpk_gt_i32 s9, 0x83
	s_cbranch_scc1 .LBB0_667
	s_bfe_u32 s14, s11, 0x30007
	s_mul_i32 s15, s14, 0x44000
	s_and_b32 s14, s10, 7
	v_mov_b32_e32 v141, v195
	s_lshl_b32 s18, s14, 3
	s_lshl_b32 s14, s9, 7
	s_movk_i32 s20, 0x880
	v_ashrrev_i32_e32 v2, 3, v141
	v_add_u32_e32 v0, s14, v2
	v_mov_b64_e32 v[4:5], s[6:7]
	s_lshr_b32 s13, s12, 6
	s_lshl_b32 s9, s12, 4
	v_mad_i64_i32 v[4:5], s[16:17], v0, s20, v[4:5]
	v_lshlrev_b32_e32 v0, 4, v141
	s_and_b32 s19, s13, 7
	s_and_b32 s13, s9, 0x380
	v_and_b32_e32 v0, 0x70, v0
	v_lshl_add_u64 v[4:5], v[4:5], 0, v[0:1]
	v_add_u32_e32 v3, s13, v2
	v_mov_b64_e32 v[6:7], s[2:3]
	s_mov_b32 s9, 0x11000
	v_mad_i64_i32 v[6:7], s[16:17], v3, s20, v[6:7]
	v_add_co_u32_e32 v8, vcc, s9, v4
	v_lshl_add_u64 v[6:7], v[6:7], 0, v[0:1]
	s_nop 0
	v_addc_co_u32_e32 v9, vcc, 0, v5, vcc
	v_add_co_u32_e32 v10, vcc, s9, v6
	s_mov_b32 s9, 0x22000
	s_nop 0
	v_addc_co_u32_e32 v11, vcc, 0, v7, vcc
	v_add_co_u32_e32 v12, vcc, s9, v4
	v_mad_u64_u32 v[130:131], s[16:17], v2, s36, v[0:1]
	s_nop 0
	v_addc_co_u32_e32 v13, vcc, 0, v5, vcc
	s_waitcnt vmcnt(22)
	v_add_co_u32_e32 v14, vcc, s9, v6
	s_mov_b32 s9, 0x33000
	s_nop 0
	v_addc_co_u32_e32 v15, vcc, 0, v7, vcc
	v_add_co_u32_e32 v16, vcc, s9, v4
	s_add_u32 s16, s28, s15
	s_nop 0
	v_addc_co_u32_e32 v17, vcc, 0, v5, vcc
	v_add_co_u32_e32 v18, vcc, s9, v6
	s_addc_u32 s17, s29, 0
	s_nop 0
	v_addc_co_u32_e32 v19, vcc, 0, v7, vcc
	global_load_dwordx4 v[42:45], v[4:5], off
	global_load_dwordx4 v[50:53], v[6:7], off
	global_load_dwordx4 v[62:65], v[8:9], off
	global_load_dwordx4 v[70:73], v[10:11], off
	global_load_dwordx4 v[78:81], v[12:13], off
	global_load_dwordx4 v[86:89], v[14:15], off
	global_load_dwordx4 v[94:97], v[16:17], off
	global_load_dwordx4 v[102:105], v[18:19], off
	global_load_dwordx4 v[46:49], v[4:5], off offset:128
	global_load_dwordx4 v[54:57], v[6:7], off offset:128
	global_load_dwordx4 v[66:69], v[8:9], off offset:128
	global_load_dwordx4 v[74:77], v[10:11], off offset:128
	global_load_dwordx4 v[82:85], v[12:13], off offset:128
	global_load_dwordx4 v[90:93], v[14:15], off offset:128
	global_load_dwordx4 v[98:101], v[16:17], off offset:128
	global_load_dwordx4 v[106:109], v[18:19], off offset:128
	s_lshl_b32 s8, s8, 3
	s_and_b32 s8, s8, 0x1ffffc0
	s_or_b32 s8, s8, s18
	s_or_b32 s8, s8, s19
	v_ashrrev_i32_e32 v3, 1, v141
	s_lshl_b32 s8, s8, 7
	v_and_b32_e32 v142, 0xffffffc0, v3
	v_ashrrev_i32_e32 v3, 31, v2
	v_mov_b64_e32 v[4:5], s[16:17]
	s_ashr_i32 s9, s8, 31
	v_mad_i64_i32 v[132:133], s[16:17], v2, s20, v[4:5]
	s_movk_i32 s19, 0x880
	v_lshl_add_u64 v[2:3], v[2:3], 0, s[8:9]
	v_mov_b64_e32 v[4:5], s[28:29]
	v_and_b32_e32 v0, 7, v141
	v_mad_u64_u32 v[134:135], s[8:9], v2, s19, v[4:5]
	v_mov_b32_e32 v2, 0
	v_and_b32_e32 v140, 64, v141
	v_lshlrev_b32_e32 v0, 4, v0
	v_mad_i32_i24 v135, v3, s19, v135
	s_mov_b32 s15, -2
	v_mov_b32_e32 v3, v2
	v_mov_b32_e32 v4, v2
	v_mov_b32_e32 v5, v2
	v_mov_b32_e32 v6, v2
	v_mov_b32_e32 v7, v2
	v_mov_b32_e32 v8, v2
	v_mov_b32_e32 v9, v2
	v_mov_b32_e32 v10, v2
	v_mov_b32_e32 v11, v2
	v_mov_b32_e32 v12, v2
	v_mov_b32_e32 v13, v2
	v_mov_b32_e32 v14, v2
	v_mov_b32_e32 v15, v2
	v_mov_b32_e32 v16, v2
	v_mov_b32_e32 v17, v2
	v_mov_b32_e32 v18, v2
	v_mov_b32_e32 v19, v2
	v_mov_b32_e32 v20, v2
	v_mov_b32_e32 v21, v2
	s_waitcnt vmcnt(37)
	v_mov_b32_e32 v22, v2
	v_mov_b32_e32 v23, v2
	v_mov_b32_e32 v24, v2
	v_mov_b32_e32 v25, v2
	v_mov_b32_e32 v26, v2
	v_mov_b32_e32 v27, v2
	v_mov_b32_e32 v28, v2
	v_mov_b32_e32 v29, v2
	s_waitcnt vmcnt(36)
	v_mov_b32_e32 v30, v2
	v_mov_b32_e32 v31, v2
	v_mov_b32_e32 v32, v2
	v_mov_b32_e32 v33, v2
	v_mov_b32_e32 v34, v2
	v_mov_b32_e32 v35, v2
	v_mov_b32_e32 v36, v2
	v_mov_b32_e32 v37, v2
	s_waitcnt vmcnt(35)
	v_mov_b32_e32 v38, v2
	v_mov_b32_e32 v39, v2
	v_mov_b32_e32 v40, v2
	v_mov_b32_e32 v41, v2
	v_mov_b32_e32 v58, v2
	v_mov_b32_e32 v59, v2
	v_mov_b32_e32 v60, v2
	v_mov_b32_e32 v61, v2
	s_waitcnt vmcnt(34)
	v_mov_b32_e32 v110, v2
	v_mov_b32_e32 v111, v2
	v_mov_b32_e32 v112, v2
	v_mov_b32_e32 v113, v2
	v_mov_b32_e32 v114, v2
	v_mov_b32_e32 v115, v2
	v_mov_b32_e32 v116, v2
	v_mov_b32_e32 v117, v2
	s_waitcnt vmcnt(33)
	v_mov_b32_e32 v118, v2
	v_mov_b32_e32 v119, v2
	v_mov_b32_e32 v120, v2
	v_mov_b32_e32 v121, v2
	v_mov_b32_e32 v122, v2
	v_mov_b32_e32 v123, v2
	v_mov_b32_e32 v124, v2
	v_mov_b32_e32 v125, v2
	s_waitcnt vmcnt(32)
	v_mov_b32_e32 v126, v2
	v_mov_b32_e32 v127, v2
	v_mov_b32_e32 v128, v2
	v_mov_b32_e32 v129, v2
	v_mov_b32_e32 v131, v195
	v_and_b32_e32 v143, 15, v131
	v_or_b32_e32 v144, v143, v140
	v_and_b32_e32 v148, 48, v131
	v_mul_u32_u24_e32 v131, 0x50, v144
	v_lshl_add_u32 v131, v131, 1, v148
	v_or_b32_e32 v143, v143, v142
	v_mad_u32_u24 v238, v143, s36, v148
	s_branch .LBB0_671
; DEV f32x4 mfma16(bf16x8 a, bf16x8 b, f32x4 c) { return __builtin_amdgcn_mfma_f32_16x16x32_bf16(a, b, c, 0, 0, 0); }
; #define G_LOAD(RA, RB, KT) { _Pragma("unroll") for (int i = 0; i < 4; i++) { \
;       RA[i] = *(const u32x4*)(Ap + (size_t)(i * 32) * lda + (KT) * 64); RB[i] = *(const u32x4*)(Bp + (size_t)(i * 32) * ldb + (KT) * 64); } }
; template <int TI, int TJ, int KS>
; DEV void mfma_lds(const bf16_t* Arows, int lda, const bf16_t* Brows, int ldb, int i0, int j0, f32x4 (&acc)[TI][TJ]) {
;     ...
;   for (int ks = 0; ks < KS; ks++) {
;     bf16x8 af[TI], bfr[TJ];
; #pragma unroll
;     for (int i = 0; i < TI; i++) af[i] = *(const bf16x8*)(Arows + (i0 + i * 16 + l15) * lda + ks * 32 + quad * 8);
; #pragma unroll
;     for (int j = 0; j < TJ; j++) bfr[j] = *(const bf16x8*)(Brows + (j0 + j * 16 + l15) * ldb + ks * 32 + quad * 8);
; #pragma unroll
;     for (int i = 0; i < TI; i++)
; #pragma unroll
;       for (int j = 0; j < TJ; j++) acc[i][j] = mfma16(af[i], bfr[j], acc[i][j]);
; template <class Epi>
; DEV void gemm_tile(const bf16_t* __restrict__ A, int lda, const bf16_t* __restrict__ Bt, int ldb, int K, int m0, int n0,
;                    Epi& epi, char* smem) {
;     ...
;     if (kt + 3 < nk) G_LOAD(ra1, rb1, kt + 3);
;     mfma_lds<4, 4, 2>(Bs, GLD, As, GLD, wn * 64, wm * 64, acc);
.LBB0_670:
	v_lshl_add_u64 v[132:133], v[132:133], 0, s[34:35]
	v_lshl_add_u64 v[134:135], v[134:135], 0, s[34:35]
	s_and_b64 vcc, exec, s[8:9]
	ds_read_b128 v[144:147], v131 offset:20480
	ds_read_b128 v[160:163], v238
	ds_read_b128 v[164:167], v238 offset:2560
	ds_read_b128 v[168:171], v238 offset:5120
	ds_read_b128 v[172:175], v238 offset:7680
	ds_read_b128 v[148:151], v131 offset:23040
	ds_read_b128 v[152:155], v131 offset:25600
	ds_read_b128 v[156:159], v131 offset:28160
	ds_read_b128 v[176:179], v238 offset:64
	ds_read_b128 v[180:183], v238 offset:2624
	s_waitcnt lgkmcnt(8)
	v_mfma_f32_16x16x32_bf16 v[126:129], v[144:147], v[160:163], v[126:129]
	s_waitcnt lgkmcnt(7)
	v_mfma_f32_16x16x32_bf16 v[122:125], v[144:147], v[164:167], v[122:125]
	s_waitcnt lgkmcnt(6)
	v_mfma_f32_16x16x32_bf16 v[118:121], v[144:147], v[168:171], v[118:121]
	s_waitcnt lgkmcnt(5)
	v_mfma_f32_16x16x32_bf16 v[114:117], v[144:147], v[172:175], v[114:117]
	ds_read_b128 v[144:147], v131 offset:20544
	s_waitcnt lgkmcnt(5)
	v_mfma_f32_16x16x32_bf16 v[110:113], v[148:151], v[160:163], v[110:113]
	v_mfma_f32_16x16x32_bf16 v[58:61], v[148:151], v[164:167], v[58:61]
	v_mfma_f32_16x16x32_bf16 v[38:41], v[148:151], v[168:171], v[38:41]
	v_mfma_f32_16x16x32_bf16 v[34:37], v[148:151], v[172:175], v[34:37]
	ds_read_b128 v[148:151], v131 offset:23104
	s_waitcnt lgkmcnt(5)
	v_mfma_f32_16x16x32_bf16 v[30:33], v[152:155], v[160:163], v[30:33]
	v_mfma_f32_16x16x32_bf16 v[26:29], v[152:155], v[164:167], v[26:29]
	v_mfma_f32_16x16x32_bf16 v[22:25], v[152:155], v[168:171], v[22:25]
	v_mfma_f32_16x16x32_bf16 v[18:21], v[152:155], v[172:175], v[18:21]
	ds_read_b128 v[152:155], v131 offset:25664
	s_waitcnt lgkmcnt(5)
	v_mfma_f32_16x16x32_bf16 v[6:9], v[156:159], v[168:171], v[6:9]
	v_mfma_f32_16x16x32_bf16 v[2:5], v[156:159], v[172:175], v[2:5]
	ds_read_b128 v[168:171], v238 offset:5184
	ds_read_b128 v[172:175], v238 offset:7744
	v_mfma_f32_16x16x32_bf16 v[14:17], v[156:159], v[160:163], v[14:17]
	v_mfma_f32_16x16x32_bf16 v[10:13], v[156:159], v[164:167], v[10:13]
	ds_read_b128 v[156:159], v131 offset:28224
	s_waitcnt lgkmcnt(5)
	v_mfma_f32_16x16x32_bf16 v[126:129], v[144:147], v[176:179], v[126:129]
	s_waitcnt lgkmcnt(4)
	v_mfma_f32_16x16x32_bf16 v[110:113], v[148:151], v[176:179], v[110:113]
	s_waitcnt lgkmcnt(3)
	v_mfma_f32_16x16x32_bf16 v[30:33], v[152:155], v[176:179], v[30:33]
	v_mfma_f32_16x16x32_bf16 v[122:125], v[144:147], v[180:183], v[122:125]
	v_mfma_f32_16x16x32_bf16 v[58:61], v[148:151], v[180:183], v[58:61]
	v_mfma_f32_16x16x32_bf16 v[26:29], v[152:155], v[180:183], v[26:29]
	s_waitcnt lgkmcnt(2)
	v_mfma_f32_16x16x32_bf16 v[118:121], v[144:147], v[168:171], v[118:121]
	v_mfma_f32_16x16x32_bf16 v[38:41], v[148:151], v[168:171], v[38:41]
	v_mfma_f32_16x16x32_bf16 v[22:25], v[152:155], v[168:171], v[22:25]
	s_waitcnt lgkmcnt(1)
	v_mfma_f32_16x16x32_bf16 v[114:117], v[144:147], v[172:175], v[114:117]
	v_mfma_f32_16x16x32_bf16 v[34:37], v[148:151], v[172:175], v[34:37]
	v_mfma_f32_16x16x32_bf16 v[18:21], v[152:155], v[172:175], v[18:21]
	s_waitcnt lgkmcnt(0)
	v_mfma_f32_16x16x32_bf16 v[14:17], v[156:159], v[176:179], v[14:17]
	v_mfma_f32_16x16x32_bf16 v[10:13], v[156:159], v[180:183], v[10:13]
	v_mfma_f32_16x16x32_bf16 v[6:9], v[156:159], v[168:171], v[6:9]
	v_mfma_f32_16x16x32_bf16 v[2:5], v[156:159], v[172:175], v[2:5]
	s_cbranch_vccnz .LBB0_675

; DEV f32x4 mfma16(bf16x8 a, bf16x8 b, f32x4 c) { return __builtin_amdgcn_mfma_f32_16x16x32_bf16(a, b, c, 0, 0, 0); }
; #define G_LOAD(RA, RB, KT) { _Pragma("unroll") for (int i = 0; i < 4; i++) { \
;       RA[i] = *(const u32x4*)(Ap + (size_t)(i * 32) * lda + (KT) * 64); RB[i] = *(const u32x4*)(Bp + (size_t)(i * 32) * ldb + (KT) * 64); } }
; #define G_STORE(RA, RB) { _Pragma("unroll") for (int i = 0; i < 4; i++) { \
;       *(u32x4*)(As + (lrow + i * 32) * GLD + lcc * 8) = RA[i]; *(u32x4*)(Bs + (lrow + i * 32) * GLD + lcc * 8) = RB[i]; } }
; template <int TI, int TJ, int KS>
; DEV void mfma_lds(const bf16_t* Arows, int lda, const bf16_t* Brows, int ldb, int i0, int j0, f32x4 (&acc)[TI][TJ]) {
;     ...
;   for (int ks = 0; ks < KS; ks++) {
;     bf16x8 af[TI], bfr[TJ];
; #pragma unroll
;     for (int i = 0; i < TI; i++) af[i] = *(const bf16x8*)(Arows + (i0 + i * 16 + l15) * lda + ks * 32 + quad * 8);
; #pragma unroll
;     for (int j = 0; j < TJ; j++) bfr[j] = *(const bf16x8*)(Brows + (j0 + j * 16 + l15) * ldb + ks * 32 + quad * 8);
; #pragma unroll
;     for (int i = 0; i < TI; i++)
; #pragma unroll
;       for (int j = 0; j < TJ; j++) acc[i][j] = mfma16(af[i], bfr[j], acc[i][j]);
; template <class Epi>
; DEV void gemm_tile(const bf16_t* __restrict__ A, int lda, const bf16_t* __restrict__ Bt, int ldb, int K, int m0, int n0,
;                    Epi& epi, char* smem) {
;     ...
;     mfma_lds<4, 4, 2>(Bs, GLD, As, GLD, wn * 64, wm * 64, acc);
;     __syncthreads();
;     G_STORE(ra1, rb1);
;     __syncthreads();
;     if (kt + 3 < nk) G_LOAD(ra1, rb1, kt + 3);
.LBB0_673:
	s_cmp_gt_u32 s15, 12
	ds_read_b128 v[144:147], v131 offset:20480
	ds_read_b128 v[160:163], v238
	ds_read_b128 v[164:167], v238 offset:2560
	ds_read_b128 v[168:171], v238 offset:5120
	ds_read_b128 v[172:175], v238 offset:7680
	ds_read_b128 v[148:151], v131 offset:23040
	ds_read_b128 v[152:155], v131 offset:25600
	ds_read_b128 v[156:159], v131 offset:28160
	ds_read_b128 v[176:179], v238 offset:64
	ds_read_b128 v[180:183], v238 offset:2624
	s_waitcnt lgkmcnt(8)
	v_mfma_f32_16x16x32_bf16 v[126:129], v[144:147], v[160:163], v[126:129]
	s_waitcnt lgkmcnt(7)
	v_mfma_f32_16x16x32_bf16 v[122:125], v[144:147], v[164:167], v[122:125]
	s_waitcnt lgkmcnt(6)
	v_mfma_f32_16x16x32_bf16 v[118:121], v[144:147], v[168:171], v[118:121]
	s_waitcnt lgkmcnt(5)
	v_mfma_f32_16x16x32_bf16 v[114:117], v[144:147], v[172:175], v[114:117]
	ds_read_b128 v[144:147], v131 offset:20544
	s_waitcnt lgkmcnt(5)
	v_mfma_f32_16x16x32_bf16 v[110:113], v[148:151], v[160:163], v[110:113]
	v_mfma_f32_16x16x32_bf16 v[58:61], v[148:151], v[164:167], v[58:61]
	v_mfma_f32_16x16x32_bf16 v[38:41], v[148:151], v[168:171], v[38:41]
	v_mfma_f32_16x16x32_bf16 v[34:37], v[148:151], v[172:175], v[34:37]
	ds_read_b128 v[148:151], v131 offset:23104
	s_waitcnt lgkmcnt(5)
	v_mfma_f32_16x16x32_bf16 v[30:33], v[152:155], v[160:163], v[30:33]
	v_mfma_f32_16x16x32_bf16 v[26:29], v[152:155], v[164:167], v[26:29]
	v_mfma_f32_16x16x32_bf16 v[22:25], v[152:155], v[168:171], v[22:25]
	v_mfma_f32_16x16x32_bf16 v[18:21], v[152:155], v[172:175], v[18:21]
	ds_read_b128 v[152:155], v131 offset:25664
	s_waitcnt lgkmcnt(5)
	v_mfma_f32_16x16x32_bf16 v[6:9], v[156:159], v[168:171], v[6:9]
	v_mfma_f32_16x16x32_bf16 v[2:5], v[156:159], v[172:175], v[2:5]
	ds_read_b128 v[168:171], v238 offset:5184
	ds_read_b128 v[172:175], v238 offset:7744
	v_mfma_f32_16x16x32_bf16 v[14:17], v[156:159], v[160:163], v[14:17]
	v_mfma_f32_16x16x32_bf16 v[10:13], v[156:159], v[164:167], v[10:13]
	ds_read_b128 v[156:159], v131 offset:28224
	s_waitcnt lgkmcnt(5)
	v_mfma_f32_16x16x32_bf16 v[126:129], v[144:147], v[176:179], v[126:129]
	s_waitcnt lgkmcnt(4)
	v_mfma_f32_16x16x32_bf16 v[110:113], v[148:151], v[176:179], v[110:113]
	s_waitcnt lgkmcnt(3)
	v_mfma_f32_16x16x32_bf16 v[30:33], v[152:155], v[176:179], v[30:33]
	v_mfma_f32_16x16x32_bf16 v[122:125], v[144:147], v[180:183], v[122:125]
	v_mfma_f32_16x16x32_bf16 v[58:61], v[148:151], v[180:183], v[58:61]
	v_mfma_f32_16x16x32_bf16 v[26:29], v[152:155], v[180:183], v[26:29]
	s_waitcnt lgkmcnt(2)
	v_mfma_f32_16x16x32_bf16 v[118:121], v[144:147], v[168:171], v[118:121]
	v_mfma_f32_16x16x32_bf16 v[38:41], v[148:151], v[168:171], v[38:41]
	v_mfma_f32_16x16x32_bf16 v[22:25], v[152:155], v[168:171], v[22:25]
	s_waitcnt lgkmcnt(1)
	v_mfma_f32_16x16x32_bf16 v[114:117], v[144:147], v[172:175], v[114:117]
	v_mfma_f32_16x16x32_bf16 v[34:37], v[148:151], v[172:175], v[34:37]
	v_mfma_f32_16x16x32_bf16 v[18:21], v[152:155], v[172:175], v[18:21]
	s_waitcnt lgkmcnt(0)
	v_mfma_f32_16x16x32_bf16 v[14:17], v[156:159], v[176:179], v[14:17]
	s_barrier
	v_mfma_f32_16x16x32_bf16 v[10:13], v[156:159], v[180:183], v[10:13]
	s_waitcnt vmcnt(8)
	ds_write_b128 v130, v[46:49]
	ds_write_b128 v130, v[54:57] offset:20480
	ds_write_b128 v130, v[66:69] offset:5120
	ds_write_b128 v130, v[74:77] offset:25600
	ds_write_b128 v130, v[82:85] offset:10240
	ds_write_b128 v130, v[90:93] offset:30720
	ds_write_b128 v130, v[98:101] offset:15360
	ds_write_b128 v130, v[106:109] offset:35840
	v_mfma_f32_16x16x32_bf16 v[6:9], v[156:159], v[168:171], v[6:9]
	s_waitcnt lgkmcnt(0)
	s_barrier
	v_mfma_f32_16x16x32_bf16 v[2:5], v[156:159], v[172:175], v[2:5]
	s_cbranch_scc1 .LBB0_670
	v_add_co_u32_e32 v46, vcc, 0x19700000, v138
	s_nop 1
	v_addc_co_u32_e32 v47, vcc, 0, v139, vcc
	v_add_co_u32_e32 v54, vcc, 0xa6e0000, v136
	global_load_dwordx4 v[46:49], v[46:47], off offset:384
	s_nop 0
	v_addc_co_u32_e32 v55, vcc, 0, v137, vcc
	v_add_co_u32_e32 v66, vcc, 0x19711000, v138
	global_load_dwordx4 v[54:57], v[54:55], off offset:384
	s_nop 0
	v_addc_co_u32_e32 v67, vcc, 0, v139, vcc
	v_add_co_u32_e32 v74, vcc, 0xa6f1000, v136
	global_load_dwordx4 v[66:69], v[66:67], off offset:384
	s_nop 0
	v_addc_co_u32_e32 v75, vcc, 0, v137, vcc
	v_add_co_u32_e32 v82, vcc, 0x19722000, v138
	global_load_dwordx4 v[74:77], v[74:75], off offset:384
	s_nop 0
	v_addc_co_u32_e32 v83, vcc, 0, v139, vcc
	v_add_co_u32_e32 v90, vcc, 0xa702000, v136
	global_load_dwordx4 v[82:85], v[82:83], off offset:384
	s_nop 0
	v_addc_co_u32_e32 v91, vcc, 0, v137, vcc
	v_add_co_u32_e32 v98, vcc, 0x19733000, v138
	global_load_dwordx4 v[90:93], v[90:91], off offset:384
	s_nop 0
	v_addc_co_u32_e32 v99, vcc, 0, v139, vcc
	v_add_co_u32_e32 v106, vcc, 0xa713000, v136
	global_load_dwordx4 v[98:101], v[98:99], off offset:384
	s_nop 0
	v_addc_co_u32_e32 v107, vcc, 0, v137, vcc
	global_load_dwordx4 v[106:109], v[106:107], off offset:384
	s_branch .LBB0_670

; DEV int tidx() { int t = threadIdx.x; asm volatile("" : "+v"(t)); return t; }
; #define G_LOAD(RA, RB, KT) { _Pragma("unroll") for (int i = 0; i < 4; i++) { \
;       RA[i] = *(const u32x4*)(Ap + (size_t)(i * 32) * lda + (KT) * 64); RB[i] = *(const u32x4*)(Bp + (size_t)(i * 32) * ldb + (KT) * 64); } }
; template <class Epi>
; DEV void gemm_tile(const bf16_t* __restrict__ A, int lda, const bf16_t* __restrict__ Bt, int ldb, int K, int m0, int n0,
;                    Epi& epi, char* smem) {
;     ...
;   const int tid = tidx(), lane = tid & 63, w = tid >> 6, wm = w >> 1, wn = w & 1;
;   const int l15 = lane & 15, quad = lane >> 4;
;   f32x4 acc[4][4];
; #pragma unroll
;   for (int i = 0; i < 4; i++)
; #pragma unroll
;     for (int j = 0; j < 4; j++) acc[i][j] = (f32x4){0.f, 0.f, 0.f, 0.f};
;   u32x4 ra0[4], rb0[4], ra1[4], rb1[4];
;   const int nk = K >> 6;
;   const int lrow = tid >> 3, lcc = tid & 7;
;   const bf16_t* Ap = A + (size_t)(m0 + lrow) * lda + lcc * 8;
;   const bf16_t* Bp = Bt + (size_t)(n0 + lrow) * ldb + lcc * 8;
;     ...
;   G_LOAD(ra0, rb0, 0);
;   G_LOAD(ra1, rb1, 1);
; DEV void phase_gemm_win(const Params& p, char* smem) {
;     ...
;   for (int item = blockIdx.x; item < items; item += gridDim.x) {
;     int mt = item / NTL, nt = item - mt * NTL;
;     gemm_tile(WSP(bf16_t, OFF_H), LDH, WSP(bf16_t, S_WIN0), LDH, 1024, mt * 128, nt * 128, epi, smem);
.LBB0_1037:
	s_mul_hi_i32 s8, s11, 0x2aaaaaab
	s_lshr_b32 s9, s8, 31
	s_ashr_i32 s8, s8, 1
	s_add_i32 s14, s8, s9
	v_mov_b32_e32 v140, v195
	s_mul_i32 s8, s14, -12
	s_lshl_b32 s12, s14, 7
	s_add_i32 s8, s8, s11
	v_ashrrev_i32_e32 v66, 3, v140
	v_add_u32_e32 v68, s12, v66
	v_mov_b64_e32 v[2:3], s[2:3]
	v_lshlrev_b32_e32 v0, 4, v140
	s_lshl_b32 s13, s8, 7
	v_mad_i64_i32 v[2:3], s[8:9], v68, s19, v[2:3]
	v_and_b32_e32 v0, 0x70, v0
	v_lshl_add_u64 v[6:7], v[2:3], 0, v[0:1]
	v_add_u32_e32 v4, s13, v66
	v_mov_b64_e32 v[2:3], s[6:7]
	v_mad_i64_i32 v[2:3], s[8:9], v4, s19, v[2:3]
	s_mov_b32 s8, 0x11000
	s_waitcnt vmcnt(5)
	v_add_co_u32_e32 v22, vcc, s8, v6
	v_lshl_add_u64 v[14:15], v[2:3], 0, v[0:1]
	s_nop 0
	v_addc_co_u32_e32 v23, vcc, 0, v7, vcc
	s_waitcnt vmcnt(4)
	v_add_co_u32_e32 v30, vcc, s8, v14
	s_mov_b32 s8, 0x22000
	s_nop 0
	v_addc_co_u32_e32 v31, vcc, 0, v15, vcc
	s_waitcnt vmcnt(3)
	v_add_co_u32_e32 v38, vcc, s8, v6
	v_ashrrev_i32_e32 v67, 1, v140
	s_nop 0
	v_addc_co_u32_e32 v39, vcc, 0, v7, vcc
	s_waitcnt vmcnt(2)
	v_add_co_u32_e32 v46, vcc, s8, v14
	s_mov_b32 s8, 0x33000
	s_nop 0
	v_addc_co_u32_e32 v47, vcc, 0, v15, vcc
	s_waitcnt vmcnt(1)
	v_add_co_u32_e32 v54, vcc, s8, v6
	s_mulk_i32 s14, 0x600
	s_nop 0
	v_addc_co_u32_e32 v55, vcc, 0, v7, vcc
	s_waitcnt vmcnt(0)
	v_add_co_u32_e32 v62, vcc, s8, v14
	v_mad_u64_u32 v[130:131], s[8:9], v66, s36, v[0:1]
	s_nop 0
	v_addc_co_u32_e32 v63, vcc, 0, v15, vcc
	global_load_dwordx4 v[2:5], v[6:7], off
	s_nop 0
	global_load_dwordx4 v[10:13], v[14:15], off
	s_nop 0
	global_load_dwordx4 v[18:21], v[22:23], off
	s_nop 0
	global_load_dwordx4 v[26:29], v[30:31], off
	s_nop 0
	global_load_dwordx4 v[34:37], v[38:39], off
	s_nop 0
	global_load_dwordx4 v[42:45], v[46:47], off
	s_nop 0
	global_load_dwordx4 v[50:53], v[54:55], off
	s_nop 0
	global_load_dwordx4 v[58:61], v[62:63], off
	s_nop 0
	global_load_dwordx4 v[6:9], v[6:7], off offset:128
	s_nop 0
	global_load_dwordx4 v[14:17], v[14:15], off offset:128
	s_nop 0
	global_load_dwordx4 v[22:25], v[22:23], off offset:128
	s_nop 0
	global_load_dwordx4 v[30:33], v[30:31], off offset:128
	s_nop 0
	global_load_dwordx4 v[38:41], v[38:39], off offset:128
	s_nop 0
	global_load_dwordx4 v[46:49], v[46:47], off offset:128
	s_nop 0
	global_load_dwordx4 v[54:57], v[54:55], off offset:128
	s_nop 0
	global_load_dwordx4 v[62:65], v[62:63], off offset:128
	v_add_u32_e32 v66, s10, v66
	v_and_b32_e32 v142, 0xffffffc0, v67
	v_and_b32_e32 v0, 7, v140
	v_subrev_u32_e32 v69, s14, v66
	v_mov_b64_e32 v[66:67], s[28:29]
	v_mov_b32_e32 v90, 0
	v_and_b32_e32 v141, 64, v140
	v_lshlrev_b32_e32 v0, 4, v0
	v_mad_i64_i32 v[132:133], s[8:9], v69, s19, v[66:67]
	v_mad_i64_i32 v[134:135], s[8:9], v68, s19, v[66:67]
	s_mov_b32 s14, -2
	v_mov_b32_e32 v91, v90
	v_mov_b32_e32 v92, v90
	v_mov_b32_e32 v93, v90
	v_mov_b32_e32 v66, v90
	v_mov_b32_e32 v67, v90
	v_mov_b32_e32 v68, v90
	v_mov_b32_e32 v69, v90
	v_mov_b32_e32 v74, v90
	v_mov_b32_e32 v75, v90
	v_mov_b32_e32 v76, v90
	v_mov_b32_e32 v77, v90
	v_mov_b32_e32 v86, v90
	v_mov_b32_e32 v87, v90
	v_mov_b32_e32 v88, v90
	v_mov_b32_e32 v89, v90
	v_mov_b32_e32 v70, v90
	v_mov_b32_e32 v71, v90
	v_mov_b32_e32 v72, v90
	v_mov_b32_e32 v73, v90
	v_mov_b32_e32 v78, v90
	v_mov_b32_e32 v79, v90
	v_mov_b32_e32 v80, v90
	v_mov_b32_e32 v81, v90
	v_mov_b32_e32 v82, v90
	v_mov_b32_e32 v83, v90
	v_mov_b32_e32 v84, v90
	v_mov_b32_e32 v85, v90
	v_mov_b32_e32 v94, v90
	v_mov_b32_e32 v95, v90
	v_mov_b32_e32 v96, v90
	v_mov_b32_e32 v97, v90
	v_mov_b32_e32 v98, v90
	v_mov_b32_e32 v99, v90
	v_mov_b32_e32 v100, v90
	v_mov_b32_e32 v101, v90
	v_mov_b32_e32 v102, v90
	v_mov_b32_e32 v103, v90
	v_mov_b32_e32 v104, v90
	v_mov_b32_e32 v105, v90
	v_mov_b32_e32 v106, v90
	v_mov_b32_e32 v107, v90
	v_mov_b32_e32 v108, v90
	v_mov_b32_e32 v109, v90
	v_mov_b32_e32 v110, v90
	v_mov_b32_e32 v111, v90
	v_mov_b32_e32 v112, v90
	v_mov_b32_e32 v113, v90
	v_mov_b32_e32 v118, v90
	v_mov_b32_e32 v119, v90
	v_mov_b32_e32 v120, v90
	v_mov_b32_e32 v121, v90
	v_mov_b32_e32 v122, v90
	v_mov_b32_e32 v123, v90
	v_mov_b32_e32 v124, v90
	v_mov_b32_e32 v125, v90
	v_mov_b32_e32 v126, v90
	v_mov_b32_e32 v127, v90
	v_mov_b32_e32 v128, v90
	v_mov_b32_e32 v129, v90
	v_mov_b32_e32 v114, v90
	v_mov_b32_e32 v115, v90
	v_mov_b32_e32 v116, v90
	v_mov_b32_e32 v117, v90
	v_mov_b32_e32 v131, v195
	v_and_b32_e32 v143, 15, v131
	v_or_b32_e32 v144, v143, v141
	v_and_b32_e32 v148, 48, v131
	v_mul_u32_u24_e32 v131, 0x50, v144
	v_lshl_add_u32 v131, v131, 1, v148
	v_or_b32_e32 v143, v143, v142
	v_mad_u32_u24 v238, v143, s36, v148
	s_branch .LBB0_1039
; DEV f32x4 mfma16(bf16x8 a, bf16x8 b, f32x4 c) { return __builtin_amdgcn_mfma_f32_16x16x32_bf16(a, b, c, 0, 0, 0); }
; #define G_LOAD(RA, RB, KT) { _Pragma("unroll") for (int i = 0; i < 4; i++) { \
;       RA[i] = *(const u32x4*)(Ap + (size_t)(i * 32) * lda + (KT) * 64); RB[i] = *(const u32x4*)(Bp + (size_t)(i * 32) * ldb + (KT) * 64); } }
; template <int TI, int TJ, int KS>
; DEV void mfma_lds(const bf16_t* Arows, int lda, const bf16_t* Brows, int ldb, int i0, int j0, f32x4 (&acc)[TI][TJ]) {
;     ...
;   for (int ks = 0; ks < KS; ks++) {
;     bf16x8 af[TI], bfr[TJ];
; #pragma unroll
;     for (int i = 0; i < TI; i++) af[i] = *(const bf16x8*)(Arows + (i0 + i * 16 + l15) * lda + ks * 32 + quad * 8);
; #pragma unroll
;     for (int j = 0; j < TJ; j++) bfr[j] = *(const bf16x8*)(Brows + (j0 + j * 16 + l15) * ldb + ks * 32 + quad * 8);
; #pragma unroll
;     for (int i = 0; i < TI; i++)
; #pragma unroll
;       for (int j = 0; j < TJ; j++) acc[i][j] = mfma16(af[i], bfr[j], acc[i][j]);
; template <class Epi>
; DEV void gemm_tile(const bf16_t* __restrict__ A, int lda, const bf16_t* __restrict__ Bt, int ldb, int K, int m0, int n0,
;                    Epi& epi, char* smem) {
;     ...
;     if (kt + 3 < nk) G_LOAD(ra1, rb1, kt + 3);
;     mfma_lds<4, 4, 2>(Bs, GLD, As, GLD, wn * 64, wm * 64, acc);
.LBB0_1038:
	v_lshl_add_u64 v[132:133], v[132:133], 0, s[34:35]
	v_lshl_add_u64 v[134:135], v[134:135], 0, s[34:35]
	s_and_b64 vcc, exec, s[8:9]
	ds_read_b128 v[148:151], v131 offset:20480
	ds_read_b128 v[164:167], v238
	ds_read_b128 v[168:171], v238 offset:2560
	ds_read_b128 v[172:175], v238 offset:5120
	ds_read_b128 v[176:179], v238 offset:7680
	ds_read_b128 v[152:155], v131 offset:23040
	ds_read_b128 v[156:159], v131 offset:25600
	ds_read_b128 v[160:163], v131 offset:28160
	ds_read_b128 v[180:183], v238 offset:64
	ds_read_b128 v[184:187], v238 offset:2624
	s_waitcnt lgkmcnt(8)
	v_mfma_f32_16x16x32_bf16 v[114:117], v[148:151], v[164:167], v[114:117]
	s_waitcnt lgkmcnt(7)
	v_mfma_f32_16x16x32_bf16 v[126:129], v[148:151], v[168:171], v[126:129]
	s_waitcnt lgkmcnt(6)
	v_mfma_f32_16x16x32_bf16 v[122:125], v[148:151], v[172:175], v[122:125]
	s_waitcnt lgkmcnt(5)
	v_mfma_f32_16x16x32_bf16 v[118:121], v[148:151], v[176:179], v[118:121]
	ds_read_b128 v[148:151], v131 offset:20544
	s_waitcnt lgkmcnt(5)
	v_mfma_f32_16x16x32_bf16 v[110:113], v[152:155], v[164:167], v[110:113]
	v_mfma_f32_16x16x32_bf16 v[106:109], v[152:155], v[168:171], v[106:109]
	v_mfma_f32_16x16x32_bf16 v[102:105], v[152:155], v[172:175], v[102:105]
	v_mfma_f32_16x16x32_bf16 v[98:101], v[152:155], v[176:179], v[98:101]
	ds_read_b128 v[152:155], v131 offset:23104
	s_waitcnt lgkmcnt(5)
	v_mfma_f32_16x16x32_bf16 v[94:97], v[156:159], v[164:167], v[94:97]
	v_mfma_f32_16x16x32_bf16 v[82:85], v[156:159], v[168:171], v[82:85]
	v_mfma_f32_16x16x32_bf16 v[78:81], v[156:159], v[172:175], v[78:81]
	v_mfma_f32_16x16x32_bf16 v[70:73], v[156:159], v[176:179], v[70:73]
	ds_read_b128 v[156:159], v131 offset:25664
	s_waitcnt lgkmcnt(5)
	v_mfma_f32_16x16x32_bf16 v[66:69], v[160:163], v[172:175], v[66:69]
	v_mfma_f32_16x16x32_bf16 v[90:93], v[160:163], v[176:179], v[90:93]
	ds_read_b128 v[172:175], v238 offset:5184
	ds_read_b128 v[176:179], v238 offset:7744
	v_mfma_f32_16x16x32_bf16 v[86:89], v[160:163], v[164:167], v[86:89]
	v_mfma_f32_16x16x32_bf16 v[74:77], v[160:163], v[168:171], v[74:77]
	ds_read_b128 v[160:163], v131 offset:28224
	s_waitcnt lgkmcnt(5)
	v_mfma_f32_16x16x32_bf16 v[114:117], v[148:151], v[180:183], v[114:117]
	s_waitcnt lgkmcnt(4)
	v_mfma_f32_16x16x32_bf16 v[110:113], v[152:155], v[180:183], v[110:113]
	s_waitcnt lgkmcnt(3)
	v_mfma_f32_16x16x32_bf16 v[94:97], v[156:159], v[180:183], v[94:97]
	v_mfma_f32_16x16x32_bf16 v[126:129], v[148:151], v[184:187], v[126:129]
	v_mfma_f32_16x16x32_bf16 v[106:109], v[152:155], v[184:187], v[106:109]
	v_mfma_f32_16x16x32_bf16 v[82:85], v[156:159], v[184:187], v[82:85]
	s_waitcnt lgkmcnt(2)
	v_mfma_f32_16x16x32_bf16 v[122:125], v[148:151], v[172:175], v[122:125]
	v_mfma_f32_16x16x32_bf16 v[102:105], v[152:155], v[172:175], v[102:105]
	v_mfma_f32_16x16x32_bf16 v[78:81], v[156:159], v[172:175], v[78:81]
	s_waitcnt lgkmcnt(1)
	v_mfma_f32_16x16x32_bf16 v[118:121], v[148:151], v[176:179], v[118:121]
	v_mfma_f32_16x16x32_bf16 v[98:101], v[152:155], v[176:179], v[98:101]
	v_mfma_f32_16x16x32_bf16 v[70:73], v[156:159], v[176:179], v[70:73]
	s_waitcnt lgkmcnt(0)
	v_mfma_f32_16x16x32_bf16 v[86:89], v[160:163], v[180:183], v[86:89]
	v_mfma_f32_16x16x32_bf16 v[74:77], v[160:163], v[184:187], v[74:77]
	v_mfma_f32_16x16x32_bf16 v[66:69], v[160:163], v[172:175], v[66:69]
	v_mfma_f32_16x16x32_bf16 v[90:93], v[160:163], v[176:179], v[90:93]
	s_cbranch_vccnz .LBB0_1043

; DEV f32x4 mfma16(bf16x8 a, bf16x8 b, f32x4 c) { return __builtin_amdgcn_mfma_f32_16x16x32_bf16(a, b, c, 0, 0, 0); }
; #define G_LOAD(RA, RB, KT) { _Pragma("unroll") for (int i = 0; i < 4; i++) { \
;       RA[i] = *(const u32x4*)(Ap + (size_t)(i * 32) * lda + (KT) * 64); RB[i] = *(const u32x4*)(Bp + (size_t)(i * 32) * ldb + (KT) * 64); } }
; #define G_STORE(RA, RB) { _Pragma("unroll") for (int i = 0; i < 4; i++) { \
;       *(u32x4*)(As + (lrow + i * 32) * GLD + lcc * 8) = RA[i]; *(u32x4*)(Bs + (lrow + i * 32) * GLD + lcc * 8) = RB[i]; } }
; template <int TI, int TJ, int KS>
; DEV void mfma_lds(const bf16_t* Arows, int lda, const bf16_t* Brows, int ldb, int i0, int j0, f32x4 (&acc)[TI][TJ]) {
;     ...
;   for (int ks = 0; ks < KS; ks++) {
;     bf16x8 af[TI], bfr[TJ];
; #pragma unroll
;     for (int i = 0; i < TI; i++) af[i] = *(const bf16x8*)(Arows + (i0 + i * 16 + l15) * lda + ks * 32 + quad * 8);
; #pragma unroll
;     for (int j = 0; j < TJ; j++) bfr[j] = *(const bf16x8*)(Brows + (j0 + j * 16 + l15) * ldb + ks * 32 + quad * 8);
; #pragma unroll
;     for (int i = 0; i < TI; i++)
; #pragma unroll
;       for (int j = 0; j < TJ; j++) acc[i][j] = mfma16(af[i], bfr[j], acc[i][j]);
; template <class Epi>
; DEV void gemm_tile(const bf16_t* __restrict__ A, int lda, const bf16_t* __restrict__ Bt, int ldb, int K, int m0, int n0,
;                    Epi& epi, char* smem) {
;     ...
;     mfma_lds<4, 4, 2>(Bs, GLD, As, GLD, wn * 64, wm * 64, acc);
;     __syncthreads();
;     G_STORE(ra1, rb1);
;     __syncthreads();
;     if (kt + 3 < nk) G_LOAD(ra1, rb1, kt + 3);
.LBB0_1041:
	s_cmp_gt_u32 s14, 12
	ds_read_b128 v[148:151], v131 offset:20480
	ds_read_b128 v[164:167], v238
	ds_read_b128 v[168:171], v238 offset:2560
	ds_read_b128 v[172:175], v238 offset:5120
	ds_read_b128 v[176:179], v238 offset:7680
	ds_read_b128 v[152:155], v131 offset:23040
	ds_read_b128 v[156:159], v131 offset:25600
	ds_read_b128 v[160:163], v131 offset:28160
	ds_read_b128 v[180:183], v238 offset:64
	ds_read_b128 v[184:187], v238 offset:2624
	s_waitcnt lgkmcnt(8)
	v_mfma_f32_16x16x32_bf16 v[114:117], v[148:151], v[164:167], v[114:117]
	s_waitcnt lgkmcnt(7)
	v_mfma_f32_16x16x32_bf16 v[126:129], v[148:151], v[168:171], v[126:129]
	s_waitcnt lgkmcnt(6)
	v_mfma_f32_16x16x32_bf16 v[122:125], v[148:151], v[172:175], v[122:125]
	s_waitcnt lgkmcnt(5)
	v_mfma_f32_16x16x32_bf16 v[118:121], v[148:151], v[176:179], v[118:121]
	ds_read_b128 v[148:151], v131 offset:20544
	s_waitcnt lgkmcnt(5)
	v_mfma_f32_16x16x32_bf16 v[110:113], v[152:155], v[164:167], v[110:113]
	v_mfma_f32_16x16x32_bf16 v[106:109], v[152:155], v[168:171], v[106:109]
	v_mfma_f32_16x16x32_bf16 v[102:105], v[152:155], v[172:175], v[102:105]
	v_mfma_f32_16x16x32_bf16 v[98:101], v[152:155], v[176:179], v[98:101]
	ds_read_b128 v[152:155], v131 offset:23104
	s_waitcnt lgkmcnt(5)
	v_mfma_f32_16x16x32_bf16 v[94:97], v[156:159], v[164:167], v[94:97]
	v_mfma_f32_16x16x32_bf16 v[82:85], v[156:159], v[168:171], v[82:85]
	v_mfma_f32_16x16x32_bf16 v[78:81], v[156:159], v[172:175], v[78:81]
	v_mfma_f32_16x16x32_bf16 v[70:73], v[156:159], v[176:179], v[70:73]
	ds_read_b128 v[156:159], v131 offset:25664
	s_waitcnt lgkmcnt(5)
	v_mfma_f32_16x16x32_bf16 v[66:69], v[160:163], v[172:175], v[66:69]
	v_mfma_f32_16x16x32_bf16 v[90:93], v[160:163], v[176:179], v[90:93]
	ds_read_b128 v[172:175], v238 offset:5184
	ds_read_b128 v[176:179], v238 offset:7744
	v_mfma_f32_16x16x32_bf16 v[86:89], v[160:163], v[164:167], v[86:89]
	v_mfma_f32_16x16x32_bf16 v[74:77], v[160:163], v[168:171], v[74:77]
	ds_read_b128 v[160:163], v131 offset:28224
	s_waitcnt lgkmcnt(5)
	v_mfma_f32_16x16x32_bf16 v[114:117], v[148:151], v[180:183], v[114:117]
	s_waitcnt lgkmcnt(4)
	v_mfma_f32_16x16x32_bf16 v[110:113], v[152:155], v[180:183], v[110:113]
	s_waitcnt lgkmcnt(3)
	v_mfma_f32_16x16x32_bf16 v[94:97], v[156:159], v[180:183], v[94:97]
	v_mfma_f32_16x16x32_bf16 v[126:129], v[148:151], v[184:187], v[126:129]
	v_mfma_f32_16x16x32_bf16 v[106:109], v[152:155], v[184:187], v[106:109]
	v_mfma_f32_16x16x32_bf16 v[82:85], v[156:159], v[184:187], v[82:85]
	s_waitcnt lgkmcnt(2)
	v_mfma_f32_16x16x32_bf16 v[122:125], v[148:151], v[172:175], v[122:125]
	v_mfma_f32_16x16x32_bf16 v[102:105], v[152:155], v[172:175], v[102:105]
	v_mfma_f32_16x16x32_bf16 v[78:81], v[156:159], v[172:175], v[78:81]
	s_waitcnt lgkmcnt(1)
	v_mfma_f32_16x16x32_bf16 v[118:121], v[148:151], v[176:179], v[118:121]
	v_mfma_f32_16x16x32_bf16 v[98:101], v[152:155], v[176:179], v[98:101]
	v_mfma_f32_16x16x32_bf16 v[70:73], v[156:159], v[176:179], v[70:73]
	s_waitcnt lgkmcnt(0)
	v_mfma_f32_16x16x32_bf16 v[86:89], v[160:163], v[180:183], v[86:89]
	s_barrier
	v_mfma_f32_16x16x32_bf16 v[74:77], v[160:163], v[184:187], v[74:77]
	s_waitcnt vmcnt(8)
	ds_write_b128 v130, v[6:9]
	ds_write_b128 v130, v[14:17] offset:20480
	ds_write_b128 v130, v[22:25] offset:5120
	ds_write_b128 v130, v[30:33] offset:25600
	ds_write_b128 v130, v[38:41] offset:10240
	ds_write_b128 v130, v[46:49] offset:30720
	ds_write_b128 v130, v[54:57] offset:15360
	ds_write_b128 v130, v[62:65] offset:35840
	v_mfma_f32_16x16x32_bf16 v[66:69], v[160:163], v[172:175], v[66:69]
	s_waitcnt lgkmcnt(0)
	s_barrier
	v_mfma_f32_16x16x32_bf16 v[90:93], v[160:163], v[176:179], v[90:93]
	s_cbranch_scc1 .LBB0_1038
	v_add_co_u32_e32 v6, vcc, 0x4200000, v138
	s_nop 1
	v_addc_co_u32_e32 v7, vcc, 0, v139, vcc
	v_add_co_u32_e32 v14, vcc, 0xa300000, v136
	global_load_dwordx4 v[6:9], v[6:7], off offset:384
	s_nop 0
	v_addc_co_u32_e32 v15, vcc, 0, v137, vcc
	v_add_co_u32_e32 v22, vcc, 0x4211000, v138
	global_load_dwordx4 v[14:17], v[14:15], off offset:384
	s_nop 0
	v_addc_co_u32_e32 v23, vcc, 0, v139, vcc
	v_add_co_u32_e32 v30, vcc, 0xa311000, v136
	global_load_dwordx4 v[22:25], v[22:23], off offset:384
	s_nop 0
	v_addc_co_u32_e32 v31, vcc, 0, v137, vcc
	v_add_co_u32_e32 v38, vcc, 0x4222000, v138
	global_load_dwordx4 v[30:33], v[30:31], off offset:384
	s_nop 0
	v_addc_co_u32_e32 v39, vcc, 0, v139, vcc
	v_add_co_u32_e32 v46, vcc, 0xa322000, v136
	global_load_dwordx4 v[38:41], v[38:39], off offset:384
	s_nop 0
	v_addc_co_u32_e32 v47, vcc, 0, v137, vcc
	v_add_co_u32_e32 v54, vcc, 0x4233000, v138
	global_load_dwordx4 v[46:49], v[46:47], off offset:384
	s_nop 0
	v_addc_co_u32_e32 v55, vcc, 0, v139, vcc
	v_add_co_u32_e32 v62, vcc, 0xa333000, v136
	global_load_dwordx4 v[54:57], v[54:55], off offset:384
	s_nop 0
	v_addc_co_u32_e32 v63, vcc, 0, v137, vcc
	global_load_dwordx4 v[62:65], v[62:63], off offset:384
	s_branch .LBB0_1038
